# C4 unrolled steps: the M0 wait state before each LDS-DMA load is filled with the step's own fragment ds_reads instead of s_nop
# speedup vs baseline: 1.0198x; 1.0029x over previous
; DI int otid() { int t = threadIdx.x; asm volatile("" : "+v"(t)); return t; }
; #define G_LOAD(RA, RB, k_) do { \
;     _Pragma("unroll") for (int i = 0; i < 4; ++i) RA[i] = *(const u32x4*)&Ap[i * sa + (k_)]; \
;     _Pragma("unroll") for (int i = 0; i < 2 * NJ; ++i) RB[i] = *(const u32x4*)&Bp[i * sbb + (k_)]; } while (0)
; template <int NJ>
; DI void gemm_core(const h16* __restrict__ A, int lda, const h16* __restrict__ Bt, int ldb, int K,
;                   floatx16 (&acc)[2][NJ], h16* As, h16* Bs) {
;   const int t = otid(), l = t & 63, w = t >> 6, wm = w >> 1, wn = w & 1, h = l >> 5, lr = l & 31;
;   u32x4 ra0[4], rb0[2 * NJ], ra1[4], rb1[2 * NJ];
;   const h16* Ap = A + (size_t)(t >> 3) * lda + (t & 7) * 8;
;   const h16* Bp = Bt + (size_t)(t >> 3) * ldb + (t & 7) * 8;
;   const size_t sa = (size_t)32 * lda, sbb = (size_t)32 * ldb;
;     ...
;   G_LOAD(ra0, rb0, 0);
;   if (64 < K) G_LOAD(ra1, rb1, 64);
;   for (int k0 = 0; k0 < K; k0 += 128) {
;     G_STEP(ra0, rb0, k0 + 128);
;     if (k0 + 64 < K) G_STEP(ra1, rb1, k0 + 192);
;   }
.LBB0_984:
	v_mov_b32_e32 v26, v152
	s_add_u32 s56, s90, s47
	v_ashrrev_i32_e32 v24, 3, v26
	v_ashrrev_i32_e32 v25, 31, v24
	v_lshlrev_b64 v[16:17], 11, v[24:25]
	v_lshlrev_b32_e32 v2, 4, v26
	v_lshl_add_u64 v[0:1], s[42:43], 0, v[16:17]
	v_and_b32_e32 v132, 0x70, v2
	v_lshl_add_u64 v[36:37], v[0:1], 0, v[132:133]
	v_add_co_u32_e32 v38, vcc, s55, v36
	v_and_b32_e32 v18, 7, v26
	s_nop 0
	v_addc_co_u32_e32 v39, vcc, 0, v37, vcc
	v_add_co_u32_e32 v40, vcc, s6, v36
	v_lshl_or_b32 v16, v18, 4, v16
	s_addc_u32 s57, s91, s53
	v_addc_co_u32_e32 v41, vcc, 0, v37, vcc
	v_lshl_add_u64 v[44:45], s[56:57], 0, v[16:17]
	v_add_co_u32_e32 v42, vcc, s7, v36
	s_nop 0
	v_addc_co_u32_e32 v43, vcc, 0, v37, vcc
	v_add_co_u32_e32 v46, vcc, s55, v44
	v_mad_u64_u32 v[32:33], s[56:57], v24, s67, v[132:133]
	s_nop 0
	v_addc_co_u32_e32 v47, vcc, 0, v45, vcc
	v_bfe_u32 v212, v152, 4, 3
	v_lshlrev_b32_e32 v212, 4, v212
	v_lshrrev_b32_e32 v213, 6, v152
	v_lshlrev_b32_e32 v213, 10, v213
	v_and_b32_e32 v214, 31, v152
	v_readfirstlane_b32 s100, v213
	v_bfe_u32 v215, v152, 5, 1
	v_bfe_u32 v216, v214, 1, 3
	v_xor_b32_e32 v216, v216, v215
	v_lshlrev_b32_e32 v216, 4, v216
	v_bfe_u32 v215, v152, 7, 1
	v_lshl_add_u32 v215, v215, 6, v214
	v_lshl_add_u32 v204, v215, 7, v216
	v_bfe_u32 v215, v152, 6, 1
	v_lshl_add_u32 v215, v215, 5, v214
	v_lshl_add_u32 v208, v215, 7, v216
	v_xor_b32_e32 v205, 32, v204
	v_xor_b32_e32 v206, 64, v204
	v_xor_b32_e32 v207, 0x60, v204
	v_xor_b32_e32 v209, 32, v208
	v_xor_b32_e32 v210, 64, v208
	v_xor_b32_e32 v211, 0x60, v208
	s_barrier
	s_add_u32 m0, s100, 2048
	v_xor_b32_e32 v36, v36, v212
	global_load_lds_dwordx4 v[36:37], off
	s_add_u32 m0, s100, 6144
	v_xor_b32_e32 v38, v38, v212
	global_load_lds_dwordx4 v[38:39], off
	s_add_u32 m0, s100, 10240
	v_xor_b32_e32 v40, v40, v212
	global_load_lds_dwordx4 v[40:41], off
	s_add_u32 m0, s100, 14336
	v_xor_b32_e32 v42, v42, v212
	global_load_lds_dwordx4 v[42:43], off
	s_add_u32 m0, s100, 18432
	v_xor_b32_e32 v44, v44, v212
	global_load_lds_dwordx4 v[44:45], off
	s_add_u32 m0, s100, 22528
	v_xor_b32_e32 v46, v46, v212
	global_load_lds_dwordx4 v[46:47], off
	s_waitcnt vmcnt(0)
	s_barrier
	s_add_u32 m0, s100, 41856
	v_and_b32_e32 v1, 31, v26
	global_load_lds_dwordx4 v[36:37], off offset:128
	s_add_u32 m0, s100, 45952
	v_lshrrev_b32_e32 v2, 1, v26
	global_load_lds_dwordx4 v[38:39], off offset:128
	s_add_u32 m0, s100, 50048
	v_and_or_b32 v3, v2, s8, v1
	global_load_lds_dwordx4 v[40:41], off offset:128
	s_add_u32 m0, s100, 54144
	v_and_b32_e32 v0, 16, v2
	global_load_lds_dwordx4 v[42:43], off offset:128
	s_add_u32 m0, s100, 58240
	v_and_or_b32 v1, v2, 32, v1
	global_load_lds_dwordx4 v[44:45], off offset:128
	s_add_u32 m0, s100, 62336
	v_mad_u64_u32 v[34:35], s[56:57], v3, s67, v[0:1]
	global_load_lds_dwordx4 v[46:47], off offset:128
	v_mad_u32_u24 v33, v1, s67, v0
	ds_read_b128 v[0:3], v204 offset:2048
	ds_read_b128 v[128:131], v205 offset:2048
	ds_read_b128 v[4:7], v204 offset:6144
	ds_read_b128 v[134:137], v205 offset:6144
	ds_read_b128 v[8:11], v208 offset:18432
	ds_read_b128 v[138:141], v209 offset:18432
	s_waitcnt lgkmcnt(1)
	v_mfma_f32_32x32x16_f16 v[16:31], v[0:3], v[8:11], 0
	v_mfma_f32_32x32x16_f16 v[0:15], v[4:7], v[8:11], 0
	ds_read_b128 v[142:145], v206 offset:6144
	ds_read_b128 v[146:149], v206 offset:2048
	ds_read_b128 v[166:169], v210 offset:18432
	s_waitcnt lgkmcnt(3)
	v_mfma_f32_32x32x16_f16 v[16:31], v[128:131], v[138:141], v[16:31]
	v_mfma_f32_32x32x16_f16 v[0:15], v[134:137], v[138:141], v[0:15]
	ds_read_b128 v[128:131], v207 offset:6144
	ds_read_b128 v[134:137], v207 offset:2048
	ds_read_b128 v[138:141], v211 offset:18432
	s_waitcnt lgkmcnt(3)
	v_mfma_f32_32x32x16_f16 v[16:31], v[146:149], v[166:169], v[16:31]
	v_mfma_f32_32x32x16_f16 v[0:15], v[142:145], v[166:169], v[0:15]
	s_waitcnt lgkmcnt(0)
	v_mfma_f32_32x32x16_f16 v[16:31], v[134:137], v[138:141], v[16:31]
	v_mfma_f32_32x32x16_f16 v[0:15], v[128:131], v[138:141], v[0:15]
	s_waitcnt vmcnt(0)
	s_barrier
	s_add_u32 m0, s100, 1792
	ds_read_b128 v[128:131], v204 offset:41984
	global_load_lds_dwordx4 v[36:37], off offset:256
	s_add_u32 m0, s100, 5888
	ds_read_b128 v[134:137], v205 offset:41984
	global_load_lds_dwordx4 v[38:39], off offset:256
	s_add_u32 m0, s100, 9984
	ds_read_b128 v[138:141], v204 offset:46080
	global_load_lds_dwordx4 v[40:41], off offset:256
	s_add_u32 m0, s100, 14080
	ds_read_b128 v[142:145], v205 offset:46080
	global_load_lds_dwordx4 v[42:43], off offset:256
	s_add_u32 m0, s100, 18176
	ds_read_b128 v[146:149], v208 offset:58368
	global_load_lds_dwordx4 v[44:45], off offset:256
	s_add_u32 m0, s100, 22272
	ds_read_b128 v[166:169], v209 offset:58368
	global_load_lds_dwordx4 v[46:47], off offset:256
	s_waitcnt lgkmcnt(1)
	v_mfma_f32_32x32x16_f16 v[16:31], v[128:131], v[146:149], v[16:31]
	v_mfma_f32_32x32x16_f16 v[0:15], v[138:141], v[146:149], v[0:15]
	ds_read_b128 v[128:131], v206 offset:46080
	ds_read_b128 v[138:141], v206 offset:41984
	ds_read_b128 v[146:149], v210 offset:58368
	s_waitcnt lgkmcnt(3)
	v_mfma_f32_32x32x16_f16 v[16:31], v[134:137], v[166:169], v[16:31]
	v_mfma_f32_32x32x16_f16 v[0:15], v[142:145], v[166:169], v[0:15]
	ds_read_b128 v[134:137], v207 offset:46080
	ds_read_b128 v[142:145], v207 offset:41984
	ds_read_b128 v[166:169], v211 offset:58368
	s_waitcnt lgkmcnt(3)
	v_mfma_f32_32x32x16_f16 v[16:31], v[138:141], v[146:149], v[16:31]
	v_mfma_f32_32x32x16_f16 v[0:15], v[128:131], v[146:149], v[0:15]
	s_waitcnt lgkmcnt(0)
	v_mfma_f32_32x32x16_f16 v[16:31], v[142:145], v[166:169], v[16:31]
	v_mfma_f32_32x32x16_f16 v[0:15], v[134:137], v[166:169], v[0:15]
	s_waitcnt vmcnt(0)
	s_barrier
; #define G_LOAD(RA, RB, k_) do { \
;     _Pragma("unroll") for (int i = 0; i < 4; ++i) RA[i] = *(const u32x4*)&Ap[i * sa + (k_)]; \
;     _Pragma("unroll") for (int i = 0; i < 2 * NJ; ++i) RB[i] = *(const u32x4*)&Bp[i * sbb + (k_)]; } while (0)
; template <int NJ>
; DI void gemm_core(const h16* __restrict__ A, int lda, const h16* __restrict__ Bt, int ldb, int K,
;                   floatx16 (&acc)[2][NJ], h16* As, h16* Bs) {
;     ...
;   G_LOAD(ra0, rb0, 0);
;   if (64 < K) G_LOAD(ra1, rb1, 64);
;   for (int k0 = 0; k0 < K; k0 += 128) {
;     G_STEP(ra0, rb0, k0 + 128);
;     if (k0 + 64 < K) G_STEP(ra1, rb1, k0 + 192);
	s_add_u32 m0, s100, 41600
	ds_read_b128 v[128:131], v204 offset:2048
	global_load_lds_dwordx4 v[36:37], off offset:384
	s_add_u32 m0, s100, 45696
	ds_read_b128 v[134:137], v205 offset:2048
	global_load_lds_dwordx4 v[38:39], off offset:384
	s_add_u32 m0, s100, 49792
	ds_read_b128 v[138:141], v204 offset:6144
	global_load_lds_dwordx4 v[40:41], off offset:384
	s_add_u32 m0, s100, 53888
	ds_read_b128 v[142:145], v205 offset:6144
	global_load_lds_dwordx4 v[42:43], off offset:384
	s_add_u32 m0, s100, 57984
	ds_read_b128 v[146:149], v208 offset:18432
	global_load_lds_dwordx4 v[44:45], off offset:384
	s_add_u32 m0, s100, 62080
	ds_read_b128 v[166:169], v209 offset:18432
	global_load_lds_dwordx4 v[46:47], off offset:384
	s_waitcnt lgkmcnt(1)
	v_mfma_f32_32x32x16_f16 v[16:31], v[128:131], v[146:149], v[16:31]
	v_mfma_f32_32x32x16_f16 v[0:15], v[138:141], v[146:149], v[0:15]
	ds_read_b128 v[128:131], v206 offset:6144
	ds_read_b128 v[138:141], v206 offset:2048
	ds_read_b128 v[146:149], v210 offset:18432
	s_waitcnt lgkmcnt(3)
	v_mfma_f32_32x32x16_f16 v[16:31], v[134:137], v[166:169], v[16:31]
	v_mfma_f32_32x32x16_f16 v[0:15], v[142:145], v[166:169], v[0:15]
	ds_read_b128 v[134:137], v207 offset:6144
	ds_read_b128 v[142:145], v207 offset:2048
	ds_read_b128 v[166:169], v211 offset:18432
	s_waitcnt lgkmcnt(3)
	v_mfma_f32_32x32x16_f16 v[16:31], v[138:141], v[146:149], v[16:31]
	v_mfma_f32_32x32x16_f16 v[0:15], v[128:131], v[146:149], v[0:15]
	s_waitcnt lgkmcnt(0)
	v_mfma_f32_32x32x16_f16 v[16:31], v[142:145], v[166:169], v[16:31]
	v_mfma_f32_32x32x16_f16 v[0:15], v[134:137], v[166:169], v[0:15]
	s_waitcnt vmcnt(0)
	s_barrier
	s_add_u32 m0, s100, 1536
	ds_read_b128 v[128:131], v204 offset:41984
	global_load_lds_dwordx4 v[36:37], off offset:512
	s_add_u32 m0, s100, 5632
	ds_read_b128 v[134:137], v205 offset:41984
	global_load_lds_dwordx4 v[38:39], off offset:512
	s_add_u32 m0, s100, 9728
	ds_read_b128 v[138:141], v204 offset:46080
	global_load_lds_dwordx4 v[40:41], off offset:512
	s_add_u32 m0, s100, 13824
	ds_read_b128 v[142:145], v205 offset:46080
	global_load_lds_dwordx4 v[42:43], off offset:512
	s_add_u32 m0, s100, 17920
	ds_read_b128 v[146:149], v208 offset:58368
	global_load_lds_dwordx4 v[44:45], off offset:512
	s_add_u32 m0, s100, 22016
	ds_read_b128 v[166:169], v209 offset:58368
	global_load_lds_dwordx4 v[46:47], off offset:512
	s_waitcnt lgkmcnt(1)
	v_mfma_f32_32x32x16_f16 v[16:31], v[128:131], v[146:149], v[16:31]
	v_mfma_f32_32x32x16_f16 v[0:15], v[138:141], v[146:149], v[0:15]
	ds_read_b128 v[128:131], v206 offset:46080
	ds_read_b128 v[138:141], v206 offset:41984
	ds_read_b128 v[146:149], v210 offset:58368
	s_waitcnt lgkmcnt(3)
	v_mfma_f32_32x32x16_f16 v[16:31], v[134:137], v[166:169], v[16:31]
	v_mfma_f32_32x32x16_f16 v[0:15], v[142:145], v[166:169], v[0:15]
	ds_read_b128 v[134:137], v207 offset:46080
	ds_read_b128 v[142:145], v207 offset:41984
	ds_read_b128 v[166:169], v211 offset:58368
	s_waitcnt lgkmcnt(3)
	v_mfma_f32_32x32x16_f16 v[16:31], v[138:141], v[146:149], v[16:31]
	v_mfma_f32_32x32x16_f16 v[0:15], v[128:131], v[146:149], v[0:15]
	s_waitcnt lgkmcnt(0)
	v_mfma_f32_32x32x16_f16 v[16:31], v[142:145], v[166:169], v[16:31]
	v_mfma_f32_32x32x16_f16 v[0:15], v[134:137], v[166:169], v[0:15]
	s_waitcnt vmcnt(0)
	s_barrier
	s_add_u32 m0, s100, 41344
	ds_read_b128 v[128:131], v204 offset:2048
	global_load_lds_dwordx4 v[36:37], off offset:640
	s_add_u32 m0, s100, 45440
	ds_read_b128 v[134:137], v205 offset:2048
	global_load_lds_dwordx4 v[38:39], off offset:640
	s_add_u32 m0, s100, 49536
	ds_read_b128 v[138:141], v204 offset:6144
	global_load_lds_dwordx4 v[40:41], off offset:640
	s_add_u32 m0, s100, 53632
	ds_read_b128 v[142:145], v205 offset:6144
	global_load_lds_dwordx4 v[42:43], off offset:640
	s_add_u32 m0, s100, 57728
	ds_read_b128 v[146:149], v208 offset:18432
	global_load_lds_dwordx4 v[44:45], off offset:640
	s_add_u32 m0, s100, 61824
	ds_read_b128 v[166:169], v209 offset:18432
	global_load_lds_dwordx4 v[46:47], off offset:640
	s_waitcnt lgkmcnt(1)
	v_mfma_f32_32x32x16_f16 v[16:31], v[128:131], v[146:149], v[16:31]
	v_mfma_f32_32x32x16_f16 v[0:15], v[138:141], v[146:149], v[0:15]
	ds_read_b128 v[128:131], v206 offset:6144
	ds_read_b128 v[138:141], v206 offset:2048
	ds_read_b128 v[146:149], v210 offset:18432
	s_waitcnt lgkmcnt(3)
	v_mfma_f32_32x32x16_f16 v[16:31], v[134:137], v[166:169], v[16:31]
	v_mfma_f32_32x32x16_f16 v[0:15], v[142:145], v[166:169], v[0:15]
	ds_read_b128 v[134:137], v207 offset:6144
	ds_read_b128 v[142:145], v207 offset:2048
	ds_read_b128 v[166:169], v211 offset:18432
	s_waitcnt lgkmcnt(3)
	v_mfma_f32_32x32x16_f16 v[16:31], v[138:141], v[146:149], v[16:31]
	v_mfma_f32_32x32x16_f16 v[0:15], v[128:131], v[146:149], v[0:15]
	s_waitcnt lgkmcnt(0)
	v_mfma_f32_32x32x16_f16 v[16:31], v[142:145], v[166:169], v[16:31]
	v_mfma_f32_32x32x16_f16 v[0:15], v[134:137], v[166:169], v[0:15]
	s_waitcnt vmcnt(0)
	s_barrier
; #define G_LOAD(RA, RB, k_) do { \
;     _Pragma("unroll") for (int i = 0; i < 4; ++i) RA[i] = *(const u32x4*)&Ap[i * sa + (k_)]; \
;     _Pragma("unroll") for (int i = 0; i < 2 * NJ; ++i) RB[i] = *(const u32x4*)&Bp[i * sbb + (k_)]; } while (0)
; template <int NJ>
; DI void gemm_core(const h16* __restrict__ A, int lda, const h16* __restrict__ Bt, int ldb, int K,
;                   floatx16 (&acc)[2][NJ], h16* As, h16* Bs) {
;     ...
;   G_LOAD(ra0, rb0, 0);
;   if (64 < K) G_LOAD(ra1, rb1, 64);
;   for (int k0 = 0; k0 < K; k0 += 128) {
;     G_STEP(ra0, rb0, k0 + 128);
;     if (k0 + 64 < K) G_STEP(ra1, rb1, k0 + 192);
	s_add_u32 m0, s100, 1280
	ds_read_b128 v[128:131], v204 offset:41984
	global_load_lds_dwordx4 v[36:37], off offset:768
	s_add_u32 m0, s100, 5376
	ds_read_b128 v[134:137], v205 offset:41984
	global_load_lds_dwordx4 v[38:39], off offset:768
	s_add_u32 m0, s100, 9472
	ds_read_b128 v[138:141], v204 offset:46080
	global_load_lds_dwordx4 v[40:41], off offset:768
	s_add_u32 m0, s100, 13568
	ds_read_b128 v[142:145], v205 offset:46080
	global_load_lds_dwordx4 v[42:43], off offset:768
	s_add_u32 m0, s100, 17664
	ds_read_b128 v[146:149], v208 offset:58368
	global_load_lds_dwordx4 v[44:45], off offset:768
	s_add_u32 m0, s100, 21760
	ds_read_b128 v[166:169], v209 offset:58368
	global_load_lds_dwordx4 v[46:47], off offset:768
	s_waitcnt lgkmcnt(1)
	v_mfma_f32_32x32x16_f16 v[16:31], v[128:131], v[146:149], v[16:31]
	v_mfma_f32_32x32x16_f16 v[0:15], v[138:141], v[146:149], v[0:15]
	ds_read_b128 v[128:131], v206 offset:46080
	ds_read_b128 v[138:141], v206 offset:41984
	ds_read_b128 v[146:149], v210 offset:58368
	s_waitcnt lgkmcnt(3)
	v_mfma_f32_32x32x16_f16 v[16:31], v[134:137], v[166:169], v[16:31]
	v_mfma_f32_32x32x16_f16 v[0:15], v[142:145], v[166:169], v[0:15]
	ds_read_b128 v[134:137], v207 offset:46080
	ds_read_b128 v[142:145], v207 offset:41984
	ds_read_b128 v[166:169], v211 offset:58368
	s_waitcnt lgkmcnt(3)
	v_mfma_f32_32x32x16_f16 v[16:31], v[138:141], v[146:149], v[16:31]
	v_mfma_f32_32x32x16_f16 v[0:15], v[128:131], v[146:149], v[0:15]
	s_waitcnt lgkmcnt(0)
	v_mfma_f32_32x32x16_f16 v[16:31], v[142:145], v[166:169], v[16:31]
	v_mfma_f32_32x32x16_f16 v[0:15], v[134:137], v[166:169], v[0:15]
	s_waitcnt vmcnt(0)
	s_barrier
	s_add_u32 m0, s100, 41088
	ds_read_b128 v[128:131], v204 offset:2048
	global_load_lds_dwordx4 v[36:37], off offset:896
	s_add_u32 m0, s100, 45184
	ds_read_b128 v[134:137], v205 offset:2048
	global_load_lds_dwordx4 v[38:39], off offset:896
	s_add_u32 m0, s100, 49280
	ds_read_b128 v[138:141], v204 offset:6144
	global_load_lds_dwordx4 v[40:41], off offset:896
	s_add_u32 m0, s100, 53376
	ds_read_b128 v[142:145], v205 offset:6144
	global_load_lds_dwordx4 v[42:43], off offset:896
	s_add_u32 m0, s100, 57472
	ds_read_b128 v[146:149], v208 offset:18432
	global_load_lds_dwordx4 v[44:45], off offset:896
	s_add_u32 m0, s100, 61568
	ds_read_b128 v[166:169], v209 offset:18432
	global_load_lds_dwordx4 v[46:47], off offset:896
	s_waitcnt lgkmcnt(1)
	v_mfma_f32_32x32x16_f16 v[16:31], v[128:131], v[146:149], v[16:31]
	v_mfma_f32_32x32x16_f16 v[0:15], v[138:141], v[146:149], v[0:15]
	ds_read_b128 v[128:131], v206 offset:6144
	ds_read_b128 v[138:141], v206 offset:2048
	ds_read_b128 v[146:149], v210 offset:18432
	s_waitcnt lgkmcnt(3)
	v_mfma_f32_32x32x16_f16 v[16:31], v[134:137], v[166:169], v[16:31]
	v_mfma_f32_32x32x16_f16 v[0:15], v[142:145], v[166:169], v[0:15]
	ds_read_b128 v[134:137], v207 offset:6144
	ds_read_b128 v[142:145], v207 offset:2048
	ds_read_b128 v[166:169], v211 offset:18432
	s_waitcnt lgkmcnt(3)
	v_mfma_f32_32x32x16_f16 v[16:31], v[138:141], v[146:149], v[16:31]
	v_mfma_f32_32x32x16_f16 v[0:15], v[128:131], v[146:149], v[0:15]
	s_waitcnt lgkmcnt(0)
	v_mfma_f32_32x32x16_f16 v[16:31], v[142:145], v[166:169], v[16:31]
	v_mfma_f32_32x32x16_f16 v[0:15], v[134:137], v[166:169], v[0:15]
	s_waitcnt vmcnt(0)
	s_barrier
	s_add_u32 m0, s100, 1024
	ds_read_b128 v[128:131], v204 offset:41984
	global_load_lds_dwordx4 v[36:37], off offset:1024
	s_add_u32 m0, s100, 5120
	ds_read_b128 v[134:137], v205 offset:41984
	global_load_lds_dwordx4 v[38:39], off offset:1024
	s_add_u32 m0, s100, 9216
	ds_read_b128 v[138:141], v204 offset:46080
	global_load_lds_dwordx4 v[40:41], off offset:1024
	s_add_u32 m0, s100, 13312
	ds_read_b128 v[142:145], v205 offset:46080
	global_load_lds_dwordx4 v[42:43], off offset:1024
	s_add_u32 m0, s100, 17408
	ds_read_b128 v[146:149], v208 offset:58368
	global_load_lds_dwordx4 v[44:45], off offset:1024
	s_add_u32 m0, s100, 21504
	ds_read_b128 v[166:169], v209 offset:58368
	global_load_lds_dwordx4 v[46:47], off offset:1024
	s_waitcnt lgkmcnt(1)
	v_mfma_f32_32x32x16_f16 v[16:31], v[128:131], v[146:149], v[16:31]
	v_mfma_f32_32x32x16_f16 v[0:15], v[138:141], v[146:149], v[0:15]
	ds_read_b128 v[128:131], v206 offset:46080
	ds_read_b128 v[138:141], v206 offset:41984
	ds_read_b128 v[146:149], v210 offset:58368
	s_waitcnt lgkmcnt(3)
	v_mfma_f32_32x32x16_f16 v[16:31], v[134:137], v[166:169], v[16:31]
	v_mfma_f32_32x32x16_f16 v[0:15], v[142:145], v[166:169], v[0:15]
	ds_read_b128 v[134:137], v207 offset:46080
	ds_read_b128 v[142:145], v207 offset:41984
	ds_read_b128 v[166:169], v211 offset:58368
	s_waitcnt lgkmcnt(3)
	v_mfma_f32_32x32x16_f16 v[16:31], v[138:141], v[146:149], v[16:31]
	v_mfma_f32_32x32x16_f16 v[0:15], v[128:131], v[146:149], v[0:15]
	s_waitcnt lgkmcnt(0)
	v_mfma_f32_32x32x16_f16 v[16:31], v[142:145], v[166:169], v[16:31]
	v_mfma_f32_32x32x16_f16 v[0:15], v[134:137], v[166:169], v[0:15]
	s_waitcnt vmcnt(0)
	s_barrier
; #define G_LOAD(RA, RB, k_) do { \
;     _Pragma("unroll") for (int i = 0; i < 4; ++i) RA[i] = *(const u32x4*)&Ap[i * sa + (k_)]; \
;     _Pragma("unroll") for (int i = 0; i < 2 * NJ; ++i) RB[i] = *(const u32x4*)&Bp[i * sbb + (k_)]; } while (0)
; template <int NJ>
; DI void gemm_core(const h16* __restrict__ A, int lda, const h16* __restrict__ Bt, int ldb, int K,
;                   floatx16 (&acc)[2][NJ], h16* As, h16* Bs) {
;     ...
;   G_LOAD(ra0, rb0, 0);
;   if (64 < K) G_LOAD(ra1, rb1, 64);
;   for (int k0 = 0; k0 < K; k0 += 128) {
;     G_STEP(ra0, rb0, k0 + 128);
;     if (k0 + 64 < K) G_STEP(ra1, rb1, k0 + 192);
	s_add_u32 m0, s100, 40832
	ds_read_b128 v[128:131], v204 offset:2048
	global_load_lds_dwordx4 v[36:37], off offset:1152
	s_add_u32 m0, s100, 44928
	ds_read_b128 v[134:137], v205 offset:2048
	global_load_lds_dwordx4 v[38:39], off offset:1152
	s_add_u32 m0, s100, 49024
	ds_read_b128 v[138:141], v204 offset:6144
	global_load_lds_dwordx4 v[40:41], off offset:1152
	s_add_u32 m0, s100, 53120
	ds_read_b128 v[142:145], v205 offset:6144
	global_load_lds_dwordx4 v[42:43], off offset:1152
	s_add_u32 m0, s100, 57216
	ds_read_b128 v[146:149], v208 offset:18432
	global_load_lds_dwordx4 v[44:45], off offset:1152
	s_add_u32 m0, s100, 61312
	ds_read_b128 v[166:169], v209 offset:18432
	global_load_lds_dwordx4 v[46:47], off offset:1152
	s_waitcnt lgkmcnt(1)
	v_mfma_f32_32x32x16_f16 v[16:31], v[128:131], v[146:149], v[16:31]
	v_mfma_f32_32x32x16_f16 v[0:15], v[138:141], v[146:149], v[0:15]
	ds_read_b128 v[128:131], v206 offset:6144
	ds_read_b128 v[138:141], v206 offset:2048
	ds_read_b128 v[146:149], v210 offset:18432
	s_waitcnt lgkmcnt(3)
	v_mfma_f32_32x32x16_f16 v[16:31], v[134:137], v[166:169], v[16:31]
	v_mfma_f32_32x32x16_f16 v[0:15], v[142:145], v[166:169], v[0:15]
	ds_read_b128 v[134:137], v207 offset:6144
	ds_read_b128 v[142:145], v207 offset:2048
	ds_read_b128 v[166:169], v211 offset:18432
	s_waitcnt lgkmcnt(3)
	v_mfma_f32_32x32x16_f16 v[16:31], v[138:141], v[146:149], v[16:31]
	v_mfma_f32_32x32x16_f16 v[0:15], v[128:131], v[146:149], v[0:15]
	s_waitcnt lgkmcnt(0)
	v_mfma_f32_32x32x16_f16 v[16:31], v[142:145], v[166:169], v[16:31]
	v_mfma_f32_32x32x16_f16 v[0:15], v[134:137], v[166:169], v[0:15]
	s_waitcnt vmcnt(0)
	s_barrier
	s_add_u32 m0, s100, 768
	ds_read_b128 v[128:131], v204 offset:41984
	global_load_lds_dwordx4 v[36:37], off offset:1280
	s_add_u32 m0, s100, 4864
	ds_read_b128 v[134:137], v205 offset:41984
	global_load_lds_dwordx4 v[38:39], off offset:1280
	s_add_u32 m0, s100, 8960
	ds_read_b128 v[138:141], v204 offset:46080
	global_load_lds_dwordx4 v[40:41], off offset:1280
	s_add_u32 m0, s100, 13056
	ds_read_b128 v[142:145], v205 offset:46080
	global_load_lds_dwordx4 v[42:43], off offset:1280
	s_add_u32 m0, s100, 17152
	ds_read_b128 v[146:149], v208 offset:58368
	global_load_lds_dwordx4 v[44:45], off offset:1280
	s_add_u32 m0, s100, 21248
	ds_read_b128 v[166:169], v209 offset:58368
	global_load_lds_dwordx4 v[46:47], off offset:1280
	s_waitcnt lgkmcnt(1)
	v_mfma_f32_32x32x16_f16 v[16:31], v[128:131], v[146:149], v[16:31]
	v_mfma_f32_32x32x16_f16 v[0:15], v[138:141], v[146:149], v[0:15]
	ds_read_b128 v[128:131], v206 offset:46080
	ds_read_b128 v[138:141], v206 offset:41984
	ds_read_b128 v[146:149], v210 offset:58368
	s_waitcnt lgkmcnt(3)
	v_mfma_f32_32x32x16_f16 v[16:31], v[134:137], v[166:169], v[16:31]
	v_mfma_f32_32x32x16_f16 v[0:15], v[142:145], v[166:169], v[0:15]
	ds_read_b128 v[134:137], v207 offset:46080
	ds_read_b128 v[142:145], v207 offset:41984
	ds_read_b128 v[166:169], v211 offset:58368
	s_waitcnt lgkmcnt(3)
	v_mfma_f32_32x32x16_f16 v[16:31], v[138:141], v[146:149], v[16:31]
	v_mfma_f32_32x32x16_f16 v[0:15], v[128:131], v[146:149], v[0:15]
	s_waitcnt lgkmcnt(0)
	v_mfma_f32_32x32x16_f16 v[16:31], v[142:145], v[166:169], v[16:31]
	v_mfma_f32_32x32x16_f16 v[0:15], v[134:137], v[166:169], v[0:15]
	s_waitcnt vmcnt(0)
	s_barrier
	s_add_u32 m0, s100, 40576
	ds_read_b128 v[128:131], v204 offset:2048
	global_load_lds_dwordx4 v[36:37], off offset:1408
	s_add_u32 m0, s100, 44672
	ds_read_b128 v[134:137], v205 offset:2048
	global_load_lds_dwordx4 v[38:39], off offset:1408
	s_add_u32 m0, s100, 48768
	ds_read_b128 v[138:141], v204 offset:6144
	global_load_lds_dwordx4 v[40:41], off offset:1408
	s_add_u32 m0, s100, 52864
	ds_read_b128 v[142:145], v205 offset:6144
	global_load_lds_dwordx4 v[42:43], off offset:1408
	s_add_u32 m0, s100, 56960
	ds_read_b128 v[146:149], v208 offset:18432
	global_load_lds_dwordx4 v[44:45], off offset:1408
	s_add_u32 m0, s100, 61056
	ds_read_b128 v[166:169], v209 offset:18432
	global_load_lds_dwordx4 v[46:47], off offset:1408
	s_waitcnt lgkmcnt(1)
	v_mfma_f32_32x32x16_f16 v[16:31], v[128:131], v[146:149], v[16:31]
	v_mfma_f32_32x32x16_f16 v[0:15], v[138:141], v[146:149], v[0:15]
	ds_read_b128 v[128:131], v206 offset:6144
	ds_read_b128 v[138:141], v206 offset:2048
	ds_read_b128 v[146:149], v210 offset:18432
	s_waitcnt lgkmcnt(3)
	v_mfma_f32_32x32x16_f16 v[16:31], v[134:137], v[166:169], v[16:31]
	v_mfma_f32_32x32x16_f16 v[0:15], v[142:145], v[166:169], v[0:15]
	ds_read_b128 v[134:137], v207 offset:6144
	ds_read_b128 v[142:145], v207 offset:2048
	ds_read_b128 v[166:169], v211 offset:18432
	s_waitcnt lgkmcnt(3)
	v_mfma_f32_32x32x16_f16 v[16:31], v[138:141], v[146:149], v[16:31]
	v_mfma_f32_32x32x16_f16 v[0:15], v[128:131], v[146:149], v[0:15]
	s_waitcnt lgkmcnt(0)
	v_mfma_f32_32x32x16_f16 v[16:31], v[142:145], v[166:169], v[16:31]
	v_mfma_f32_32x32x16_f16 v[0:15], v[134:137], v[166:169], v[0:15]
	s_waitcnt vmcnt(0)
	s_barrier
; #define G_LOAD(RA, RB, k_) do { \
;     _Pragma("unroll") for (int i = 0; i < 4; ++i) RA[i] = *(const u32x4*)&Ap[i * sa + (k_)]; \
;     _Pragma("unroll") for (int i = 0; i < 2 * NJ; ++i) RB[i] = *(const u32x4*)&Bp[i * sbb + (k_)]; } while (0)
; template <int NJ>
; DI void gemm_core(const h16* __restrict__ A, int lda, const h16* __restrict__ Bt, int ldb, int K,
;                   floatx16 (&acc)[2][NJ], h16* As, h16* Bs) {
;     ...
;   G_LOAD(ra0, rb0, 0);
;   if (64 < K) G_LOAD(ra1, rb1, 64);
;   for (int k0 = 0; k0 < K; k0 += 128) {
;     G_STEP(ra0, rb0, k0 + 128);
;     if (k0 + 64 < K) G_STEP(ra1, rb1, k0 + 192);
	s_add_u32 m0, s100, 512
	ds_read_b128 v[128:131], v204 offset:41984
	global_load_lds_dwordx4 v[36:37], off offset:1536
	s_add_u32 m0, s100, 4608
	ds_read_b128 v[134:137], v205 offset:41984
	global_load_lds_dwordx4 v[38:39], off offset:1536
	s_add_u32 m0, s100, 8704
	ds_read_b128 v[138:141], v204 offset:46080
	global_load_lds_dwordx4 v[40:41], off offset:1536
	s_add_u32 m0, s100, 12800
	ds_read_b128 v[142:145], v205 offset:46080
	global_load_lds_dwordx4 v[42:43], off offset:1536
	s_add_u32 m0, s100, 16896
	ds_read_b128 v[146:149], v208 offset:58368
	global_load_lds_dwordx4 v[44:45], off offset:1536
	s_add_u32 m0, s100, 20992
	ds_read_b128 v[166:169], v209 offset:58368
	global_load_lds_dwordx4 v[46:47], off offset:1536
	s_waitcnt lgkmcnt(1)
	v_mfma_f32_32x32x16_f16 v[16:31], v[128:131], v[146:149], v[16:31]
	v_mfma_f32_32x32x16_f16 v[0:15], v[138:141], v[146:149], v[0:15]
	ds_read_b128 v[128:131], v206 offset:46080
	ds_read_b128 v[138:141], v206 offset:41984
	ds_read_b128 v[146:149], v210 offset:58368
	s_waitcnt lgkmcnt(3)
	v_mfma_f32_32x32x16_f16 v[16:31], v[134:137], v[166:169], v[16:31]
	v_mfma_f32_32x32x16_f16 v[0:15], v[142:145], v[166:169], v[0:15]
	ds_read_b128 v[134:137], v207 offset:46080
	ds_read_b128 v[142:145], v207 offset:41984
	ds_read_b128 v[166:169], v211 offset:58368
	s_waitcnt lgkmcnt(3)
	v_mfma_f32_32x32x16_f16 v[16:31], v[138:141], v[146:149], v[16:31]
	v_mfma_f32_32x32x16_f16 v[0:15], v[128:131], v[146:149], v[0:15]
	s_waitcnt lgkmcnt(0)
	v_mfma_f32_32x32x16_f16 v[16:31], v[142:145], v[166:169], v[16:31]
	v_mfma_f32_32x32x16_f16 v[0:15], v[134:137], v[166:169], v[0:15]
	s_waitcnt vmcnt(0)
	s_barrier
	s_add_u32 m0, s100, 40320
	ds_read_b128 v[128:131], v204 offset:2048
	global_load_lds_dwordx4 v[36:37], off offset:1664
	s_add_u32 m0, s100, 44416
	ds_read_b128 v[134:137], v205 offset:2048
	global_load_lds_dwordx4 v[38:39], off offset:1664
	s_add_u32 m0, s100, 48512
	ds_read_b128 v[138:141], v204 offset:6144
	global_load_lds_dwordx4 v[40:41], off offset:1664
	s_add_u32 m0, s100, 52608
	ds_read_b128 v[142:145], v205 offset:6144
	global_load_lds_dwordx4 v[42:43], off offset:1664
	s_add_u32 m0, s100, 56704
	ds_read_b128 v[146:149], v208 offset:18432
	global_load_lds_dwordx4 v[44:45], off offset:1664
	s_add_u32 m0, s100, 60800
	ds_read_b128 v[166:169], v209 offset:18432
	global_load_lds_dwordx4 v[46:47], off offset:1664
	s_waitcnt lgkmcnt(1)
	v_mfma_f32_32x32x16_f16 v[16:31], v[128:131], v[146:149], v[16:31]
	v_mfma_f32_32x32x16_f16 v[0:15], v[138:141], v[146:149], v[0:15]
	ds_read_b128 v[128:131], v206 offset:6144
	ds_read_b128 v[138:141], v206 offset:2048
	ds_read_b128 v[146:149], v210 offset:18432
	s_waitcnt lgkmcnt(3)
	v_mfma_f32_32x32x16_f16 v[16:31], v[134:137], v[166:169], v[16:31]
	v_mfma_f32_32x32x16_f16 v[0:15], v[142:145], v[166:169], v[0:15]
	ds_read_b128 v[134:137], v207 offset:6144
	ds_read_b128 v[142:145], v207 offset:2048
	ds_read_b128 v[166:169], v211 offset:18432
	s_waitcnt lgkmcnt(3)
	v_mfma_f32_32x32x16_f16 v[16:31], v[138:141], v[146:149], v[16:31]
	v_mfma_f32_32x32x16_f16 v[0:15], v[128:131], v[146:149], v[0:15]
	s_waitcnt lgkmcnt(0)
	v_mfma_f32_32x32x16_f16 v[16:31], v[142:145], v[166:169], v[16:31]
	v_mfma_f32_32x32x16_f16 v[0:15], v[134:137], v[166:169], v[0:15]
	s_waitcnt vmcnt(0)
	s_barrier
	s_add_u32 m0, s100, 256
	s_nop 0
	global_load_lds_dwordx4 v[36:37], off offset:1792
	s_add_u32 m0, s100, 4352
	s_nop 0
	global_load_lds_dwordx4 v[38:39], off offset:1792
	s_add_u32 m0, s100, 8448
	s_nop 0
	global_load_lds_dwordx4 v[40:41], off offset:1792
	s_add_u32 m0, s100, 12544
	s_nop 0
	global_load_lds_dwordx4 v[42:43], off offset:1792
	s_add_u32 m0, s100, 16640
	s_nop 0
	global_load_lds_dwordx4 v[44:45], off offset:1792
	s_add_u32 m0, s100, 20736
	ds_read_b128 v[60:63], v204 offset:41984
	global_load_lds_dwordx4 v[46:47], off offset:1792
	ds_read_b128 v[96:99], v205 offset:41984
	ds_read_b128 v[100:103], v204 offset:46080
	ds_read_b128 v[128:131], v205 offset:46080
	ds_read_b128 v[134:137], v208 offset:58368
	ds_read_b128 v[138:141], v209 offset:58368
	s_waitcnt lgkmcnt(1)
	v_mfma_f32_32x32x16_f16 v[16:31], v[60:63], v[134:137], v[16:31]
	v_mfma_f32_32x32x16_f16 v[0:15], v[100:103], v[134:137], v[0:15]
	ds_read_b128 v[60:63], v206 offset:46080
	ds_read_b128 v[100:103], v206 offset:41984
	ds_read_b128 v[134:137], v210 offset:58368
	s_waitcnt lgkmcnt(3)
	v_mfma_f32_32x32x16_f16 v[16:31], v[96:99], v[138:141], v[16:31]
	v_mfma_f32_32x32x16_f16 v[0:15], v[128:131], v[138:141], v[0:15]
	ds_read_b128 v[96:99], v207 offset:46080
	ds_read_b128 v[128:131], v207 offset:41984
	ds_read_b128 v[138:141], v211 offset:58368
	s_waitcnt lgkmcnt(3)
	v_mfma_f32_32x32x16_f16 v[16:31], v[100:103], v[134:137], v[16:31]
	v_mfma_f32_32x32x16_f16 v[0:15], v[60:63], v[134:137], v[0:15]
	s_waitcnt lgkmcnt(0)
	v_mfma_f32_32x32x16_f16 v[16:31], v[128:131], v[138:141], v[16:31]
	v_mfma_f32_32x32x16_f16 v[0:15], v[96:99], v[138:141], v[0:15]
	s_waitcnt vmcnt(0)
	s_barrier
; #define G_LOAD(RA, RB, k_) do { \
;     _Pragma("unroll") for (int i = 0; i < 4; ++i) RA[i] = *(const u32x4*)&Ap[i * sa + (k_)]; \
;     _Pragma("unroll") for (int i = 0; i < 2 * NJ; ++i) RB[i] = *(const u32x4*)&Bp[i * sbb + (k_)]; } while (0)
; template <int NJ>
; DI void gemm_core(const h16* __restrict__ A, int lda, const h16* __restrict__ Bt, int ldb, int K,
;                   floatx16 (&acc)[2][NJ], h16* As, h16* Bs) {
;     ...
;   G_LOAD(ra0, rb0, 0);
;   if (64 < K) G_LOAD(ra1, rb1, 64);
;   for (int k0 = 0; k0 < K; k0 += 128) {
;     G_STEP(ra0, rb0, k0 + 128);
;     if (k0 + 64 < K) G_STEP(ra1, rb1, k0 + 192);
;   }
; __global__ void __launch_bounds__(256, 2) mega(Params p) {
;     ...
;         const h16* br = b == 0 ? aout : (b == 1 ? bout : cout_);
;         gemm_core<1>(br + (size_t)m0 * 512, 512, Wt + WT_BR + (size_t)(b * 1024 + n0) * 512, 512, 512, ap, As, Bs);
	s_add_u32 m0, s100, 40064
	ds_read_b128 v[60:63], v204 offset:2048
	global_load_lds_dwordx4 v[36:37], off offset:1920
	s_add_u32 m0, s100, 44160
	ds_read_b128 v[96:99], v205 offset:2048
	global_load_lds_dwordx4 v[38:39], off offset:1920
	s_add_u32 m0, s100, 48256
	ds_read_b128 v[100:103], v204 offset:6144
	global_load_lds_dwordx4 v[40:41], off offset:1920
	s_add_u32 m0, s100, 52352
	ds_read_b128 v[104:107], v205 offset:6144
	global_load_lds_dwordx4 v[42:43], off offset:1920
	s_add_u32 m0, s100, 56448
	ds_read_b128 v[108:111], v208 offset:18432
	global_load_lds_dwordx4 v[44:45], off offset:1920
	s_add_u32 m0, s100, 60544
	ds_read_b128 v[112:115], v209 offset:18432
	global_load_lds_dwordx4 v[46:47], off offset:1920
	s_waitcnt lgkmcnt(1)
	v_mfma_f32_32x32x16_f16 v[16:31], v[60:63], v[108:111], v[16:31]
	v_mfma_f32_32x32x16_f16 v[0:15], v[100:103], v[108:111], v[0:15]
	ds_read_b128 v[60:63], v206 offset:6144
	ds_read_b128 v[100:103], v206 offset:2048
	ds_read_b128 v[108:111], v210 offset:18432
	s_waitcnt lgkmcnt(3)
	v_mfma_f32_32x32x16_f16 v[16:31], v[96:99], v[112:115], v[16:31]
	v_mfma_f32_32x32x16_f16 v[0:15], v[104:107], v[112:115], v[0:15]
	ds_read_b128 v[96:99], v207 offset:6144
	ds_read_b128 v[104:107], v207 offset:2048
	ds_read_b128 v[112:115], v211 offset:18432
	s_waitcnt lgkmcnt(3)
	v_mfma_f32_32x32x16_f16 v[16:31], v[100:103], v[108:111], v[16:31]
	v_mfma_f32_32x32x16_f16 v[0:15], v[60:63], v[108:111], v[0:15]
	s_waitcnt lgkmcnt(0)
	v_mfma_f32_32x32x16_f16 v[16:31], v[104:107], v[112:115], v[16:31]
	v_mfma_f32_32x32x16_f16 v[0:15], v[96:99], v[112:115], v[0:15]
	s_waitcnt vmcnt(0)
	s_barrier
	ds_read_b128 v[36:39], v204 offset:41984
	ds_read_b128 v[40:43], v205 offset:41984
	ds_read_b128 v[44:47], v204 offset:46080
	ds_read_b128 v[48:51], v205 offset:46080
	ds_read_b128 v[52:55], v208 offset:58368
	ds_read_b128 v[56:59], v209 offset:58368
	s_waitcnt lgkmcnt(1)
	v_mfma_f32_32x32x16_f16 v[16:31], v[36:39], v[52:55], v[16:31]
	v_mfma_f32_32x32x16_f16 v[0:15], v[44:47], v[52:55], v[0:15]
	ds_read_b128 v[36:39], v206 offset:46080
	ds_read_b128 v[44:47], v206 offset:41984
	ds_read_b128 v[52:55], v210 offset:58368
	s_waitcnt lgkmcnt(3)
	v_mfma_f32_32x32x16_f16 v[16:31], v[40:43], v[56:59], v[16:31]
	v_mfma_f32_32x32x16_f16 v[0:15], v[48:51], v[56:59], v[0:15]
	ds_read_b128 v[40:43], v207 offset:46080
	ds_read_b128 v[48:51], v207 offset:41984
	ds_read_b128 v[32:35], v211 offset:58368
	s_waitcnt lgkmcnt(3)
	v_mfma_f32_32x32x16_f16 v[16:31], v[44:47], v[52:55], v[16:31]
	v_mfma_f32_32x32x16_f16 v[0:15], v[36:39], v[52:55], v[0:15]
	s_waitcnt lgkmcnt(0)
	v_mfma_f32_32x32x16_f16 v[16:31], v[48:51], v[32:35], v[16:31]
	v_mfma_f32_32x32x16_f16 v[0:15], v[40:43], v[32:35], v[0:15]
	s_cmp_eq_u32 s64, 1
	v_readlane_b32 s10, v234, 35
	s_cselect_b32 s56, s10, s38
	v_readlane_b32 s10, v234, 36
	s_cselect_b32 s57, s10, s39
	s_cmp_eq_u32 s64, 0
	v_mov_b32_e32 v58, v152
	s_cselect_b32 s56, s4, s56
	s_cselect_b32 s57, s5, s57
	v_ashrrev_i32_e32 v56, 3, v58
	s_add_u32 s56, s56, s61
	v_ashrrev_i32_e32 v57, 31, v56
	s_addc_u32 s57, s57, 0
	v_lshlrev_b64 v[48:49], 10, v[56:57]
	v_lshlrev_b32_e32 v34, 4, v58
	v_lshl_add_u64 v[32:33], s[56:57], 0, v[48:49]
	v_and_b32_e32 v132, 0x70, v34
	v_lshl_add_u64 v[100:101], v[32:33], 0, v[132:133]
	v_add_co_u32_e32 v102, vcc, s81, v100
	v_and_b32_e32 v50, 7, v58
	s_nop 0
	v_addc_co_u32_e32 v103, vcc, 0, v101, vcc
	v_add_co_u32_e32 v104, vcc, s55, v100
	s_add_u32 s56, s90, s44
	s_nop 0
	v_addc_co_u32_e32 v105, vcc, 0, v101, vcc
	v_add_co_u32_e32 v106, vcc, s9, v100
	v_lshl_or_b32 v48, v50, 4, v48
	s_addc_u32 s57, s91, s45
	v_addc_co_u32_e32 v107, vcc, 0, v101, vcc
	v_lshl_add_u64 v[52:53], s[56:57], 0, v[48:49]
	s_mov_b32 s56, 0xc40000
	v_add_co_u32_e32 v108, vcc, s56, v52
	v_addc_co_u32_e32 v109, vcc, 0, v53, vcc
	s_mov_b32 s56, 0xc48000
	v_add_co_u32_e32 v110, vcc, s56, v52
	s_nop 0
	v_addc_co_u32_e32 v111, vcc, 0, v53, vcc
	v_mad_u64_u32 v[96:97], s[56:57], v56, s67, v[132:133]
	v_bfe_u32 v212, v152, 4, 3
	v_lshlrev_b32_e32 v212, 4, v212
	v_lshrrev_b32_e32 v213, 6, v152
	v_lshlrev_b32_e32 v213, 10, v213
	v_and_b32_e32 v214, 31, v152
	v_readfirstlane_b32 s100, v213
	v_bfe_u32 v215, v152, 5, 1
	v_bfe_u32 v216, v214, 1, 3
	v_xor_b32_e32 v216, v216, v215
	v_lshlrev_b32_e32 v216, 4, v216
	v_bfe_u32 v215, v152, 7, 1
	v_lshl_add_u32 v215, v215, 6, v214
	v_lshl_add_u32 v204, v215, 7, v216
	v_bfe_u32 v215, v152, 6, 1
	v_lshl_add_u32 v215, v215, 5, v214
	v_lshl_add_u32 v208, v215, 7, v216
	v_xor_b32_e32 v205, 32, v204
	v_xor_b32_e32 v206, 64, v204
	v_xor_b32_e32 v207, 0x60, v204
	v_xor_b32_e32 v209, 32, v208
	v_xor_b32_e32 v210, 64, v208
	v_xor_b32_e32 v211, 0x60, v208
	s_barrier
	s_add_u32 m0, s100, 2048
	v_xor_b32_e32 v100, v100, v212
	global_load_lds_dwordx4 v[100:101], off
	s_add_u32 m0, s100, 6144
	v_xor_b32_e32 v102, v102, v212
	global_load_lds_dwordx4 v[102:103], off
	s_add_u32 m0, s100, 10240
	v_xor_b32_e32 v104, v104, v212
	global_load_lds_dwordx4 v[104:105], off
	s_add_u32 m0, s100, 14336
	v_xor_b32_e32 v106, v106, v212
	global_load_lds_dwordx4 v[106:107], off
	s_add_u32 m0, s100, 18432
	v_xor_b32_e32 v108, v108, v212
	global_load_lds_dwordx4 v[108:109], off
	s_add_u32 m0, s100, 22528
	v_xor_b32_e32 v110, v110, v212
	global_load_lds_dwordx4 v[110:111], off
	s_waitcnt vmcnt(0)
	s_barrier
; #define G_LOAD(RA, RB, k_) do { \
;     _Pragma("unroll") for (int i = 0; i < 4; ++i) RA[i] = *(const u32x4*)&Ap[i * sa + (k_)]; \
;     _Pragma("unroll") for (int i = 0; i < 2 * NJ; ++i) RB[i] = *(const u32x4*)&Bp[i * sbb + (k_)]; } while (0)
; template <int NJ>
; DI void gemm_core(const h16* __restrict__ A, int lda, const h16* __restrict__ Bt, int ldb, int K,
;                   floatx16 (&acc)[2][NJ], h16* As, h16* Bs) {
;     ...
;   G_LOAD(ra0, rb0, 0);
;   if (64 < K) G_LOAD(ra1, rb1, 64);
;   for (int k0 = 0; k0 < K; k0 += 128) {
;     G_STEP(ra0, rb0, k0 + 128);
;     if (k0 + 64 < K) G_STEP(ra1, rb1, k0 + 192);
	s_add_u32 m0, s100, 41856
	v_and_b32_e32 v33, 31, v58
	global_load_lds_dwordx4 v[100:101], off offset:128
	s_add_u32 m0, s100, 45952
	v_lshrrev_b32_e32 v34, 1, v58
	global_load_lds_dwordx4 v[102:103], off offset:128
	s_add_u32 m0, s100, 50048
	v_and_or_b32 v35, v34, s8, v33
	global_load_lds_dwordx4 v[104:105], off offset:128
	s_add_u32 m0, s100, 54144
	v_and_b32_e32 v32, 16, v34
	global_load_lds_dwordx4 v[106:107], off offset:128
	s_add_u32 m0, s100, 58240
	v_and_or_b32 v33, v34, 32, v33
	global_load_lds_dwordx4 v[108:109], off offset:128
	s_add_u32 m0, s100, 62336
	v_mad_u64_u32 v[98:99], s[56:57], v35, s67, v[32:33]
	global_load_lds_dwordx4 v[110:111], off offset:128
	v_mad_u32_u24 v132, v33, s67, v32
	ds_read_b128 v[32:35], v204 offset:2048
	ds_read_b128 v[178:181], v205 offset:2048
	ds_read_b128 v[36:39], v204 offset:6144
	ds_read_b128 v[182:185], v205 offset:6144
	ds_read_b128 v[40:43], v208 offset:18432
	ds_read_b128 v[186:189], v209 offset:18432
	s_waitcnt lgkmcnt(1)
	v_mfma_f32_32x32x16_f16 v[48:63], v[32:35], v[40:43], 0
	v_mfma_f32_32x32x16_f16 v[32:47], v[36:39], v[40:43], 0
	ds_read_b128 v[190:193], v206 offset:6144
	ds_read_b128 v[194:197], v206 offset:2048
	ds_read_b128 v[198:201], v210 offset:18432
	s_waitcnt lgkmcnt(3)
	v_mfma_f32_32x32x16_f16 v[48:63], v[178:181], v[186:189], v[48:63]
	v_mfma_f32_32x32x16_f16 v[32:47], v[182:185], v[186:189], v[32:47]
	ds_read_b128 v[178:181], v207 offset:6144
	ds_read_b128 v[182:185], v207 offset:2048
	ds_read_b128 v[186:189], v211 offset:18432
	s_waitcnt lgkmcnt(3)
	v_mfma_f32_32x32x16_f16 v[48:63], v[194:197], v[198:201], v[48:63]
	v_mfma_f32_32x32x16_f16 v[32:47], v[190:193], v[198:201], v[32:47]
	s_waitcnt lgkmcnt(0)
	v_mfma_f32_32x32x16_f16 v[48:63], v[182:185], v[186:189], v[48:63]
	v_mfma_f32_32x32x16_f16 v[32:47], v[178:181], v[186:189], v[32:47]
	s_waitcnt vmcnt(0)
	s_barrier
	s_add_u32 m0, s100, 1792
	ds_read_b128 v[178:181], v204 offset:41984
	global_load_lds_dwordx4 v[100:101], off offset:256
	s_add_u32 m0, s100, 5888
	ds_read_b128 v[182:185], v205 offset:41984
	global_load_lds_dwordx4 v[102:103], off offset:256
	s_add_u32 m0, s100, 9984
	ds_read_b128 v[186:189], v204 offset:46080
	global_load_lds_dwordx4 v[104:105], off offset:256
	s_add_u32 m0, s100, 14080
	ds_read_b128 v[190:193], v205 offset:46080
	global_load_lds_dwordx4 v[106:107], off offset:256
	s_add_u32 m0, s100, 18176
	ds_read_b128 v[194:197], v208 offset:58368
	global_load_lds_dwordx4 v[108:109], off offset:256
	s_add_u32 m0, s100, 22272
	ds_read_b128 v[198:201], v209 offset:58368
	global_load_lds_dwordx4 v[110:111], off offset:256
	s_waitcnt lgkmcnt(1)
	v_mfma_f32_32x32x16_f16 v[48:63], v[178:181], v[194:197], v[48:63]
	v_mfma_f32_32x32x16_f16 v[32:47], v[186:189], v[194:197], v[32:47]
	ds_read_b128 v[178:181], v206 offset:46080
	ds_read_b128 v[186:189], v206 offset:41984
	ds_read_b128 v[194:197], v210 offset:58368
	s_waitcnt lgkmcnt(3)
	v_mfma_f32_32x32x16_f16 v[48:63], v[182:185], v[198:201], v[48:63]
	v_mfma_f32_32x32x16_f16 v[32:47], v[190:193], v[198:201], v[32:47]
	ds_read_b128 v[182:185], v207 offset:46080
	ds_read_b128 v[190:193], v207 offset:41984
	ds_read_b128 v[198:201], v211 offset:58368
	s_waitcnt lgkmcnt(3)
	v_mfma_f32_32x32x16_f16 v[48:63], v[186:189], v[194:197], v[48:63]
	v_mfma_f32_32x32x16_f16 v[32:47], v[178:181], v[194:197], v[32:47]
	s_waitcnt lgkmcnt(0)
	v_mfma_f32_32x32x16_f16 v[48:63], v[190:193], v[198:201], v[48:63]
	v_mfma_f32_32x32x16_f16 v[32:47], v[182:185], v[198:201], v[32:47]
	s_waitcnt vmcnt(0)
	s_barrier
	s_add_u32 m0, s100, 41600
	ds_read_b128 v[178:181], v204 offset:2048
	global_load_lds_dwordx4 v[100:101], off offset:384
	s_add_u32 m0, s100, 45696
	ds_read_b128 v[182:185], v205 offset:2048
	global_load_lds_dwordx4 v[102:103], off offset:384
	s_add_u32 m0, s100, 49792
	ds_read_b128 v[186:189], v204 offset:6144
	global_load_lds_dwordx4 v[104:105], off offset:384
	s_add_u32 m0, s100, 53888
	ds_read_b128 v[190:193], v205 offset:6144
	global_load_lds_dwordx4 v[106:107], off offset:384
	s_add_u32 m0, s100, 57984
	ds_read_b128 v[194:197], v208 offset:18432
	global_load_lds_dwordx4 v[108:109], off offset:384
	s_add_u32 m0, s100, 62080
	ds_read_b128 v[198:201], v209 offset:18432
	global_load_lds_dwordx4 v[110:111], off offset:384
	s_waitcnt lgkmcnt(1)
	v_mfma_f32_32x32x16_f16 v[48:63], v[178:181], v[194:197], v[48:63]
	v_mfma_f32_32x32x16_f16 v[32:47], v[186:189], v[194:197], v[32:47]
	ds_read_b128 v[178:181], v206 offset:6144
	ds_read_b128 v[186:189], v206 offset:2048
	ds_read_b128 v[194:197], v210 offset:18432
	s_waitcnt lgkmcnt(3)
	v_mfma_f32_32x32x16_f16 v[48:63], v[182:185], v[198:201], v[48:63]
	v_mfma_f32_32x32x16_f16 v[32:47], v[190:193], v[198:201], v[32:47]
	ds_read_b128 v[182:185], v207 offset:6144
	ds_read_b128 v[190:193], v207 offset:2048
	ds_read_b128 v[198:201], v211 offset:18432
	s_waitcnt lgkmcnt(3)
	v_mfma_f32_32x32x16_f16 v[48:63], v[186:189], v[194:197], v[48:63]
	v_mfma_f32_32x32x16_f16 v[32:47], v[178:181], v[194:197], v[32:47]
	s_waitcnt lgkmcnt(0)
	v_mfma_f32_32x32x16_f16 v[48:63], v[190:193], v[198:201], v[48:63]
	v_mfma_f32_32x32x16_f16 v[32:47], v[182:185], v[198:201], v[32:47]
	s_waitcnt vmcnt(0)
	s_barrier
; #define G_LOAD(RA, RB, k_) do { \
;     _Pragma("unroll") for (int i = 0; i < 4; ++i) RA[i] = *(const u32x4*)&Ap[i * sa + (k_)]; \
;     _Pragma("unroll") for (int i = 0; i < 2 * NJ; ++i) RB[i] = *(const u32x4*)&Bp[i * sbb + (k_)]; } while (0)
; template <int NJ>
; DI void gemm_core(const h16* __restrict__ A, int lda, const h16* __restrict__ Bt, int ldb, int K,
;                   floatx16 (&acc)[2][NJ], h16* As, h16* Bs) {
;     ...
;   G_LOAD(ra0, rb0, 0);
;   if (64 < K) G_LOAD(ra1, rb1, 64);
;   for (int k0 = 0; k0 < K; k0 += 128) {
;     G_STEP(ra0, rb0, k0 + 128);
;     if (k0 + 64 < K) G_STEP(ra1, rb1, k0 + 192);
	s_add_u32 m0, s100, 1536
	ds_read_b128 v[178:181], v204 offset:41984
	global_load_lds_dwordx4 v[100:101], off offset:512
	s_add_u32 m0, s100, 5632
	ds_read_b128 v[182:185], v205 offset:41984
	global_load_lds_dwordx4 v[102:103], off offset:512
	s_add_u32 m0, s100, 9728
	ds_read_b128 v[186:189], v204 offset:46080
	global_load_lds_dwordx4 v[104:105], off offset:512
	s_add_u32 m0, s100, 13824
	ds_read_b128 v[190:193], v205 offset:46080
	global_load_lds_dwordx4 v[106:107], off offset:512
	s_add_u32 m0, s100, 17920
	ds_read_b128 v[194:197], v208 offset:58368
	global_load_lds_dwordx4 v[108:109], off offset:512
	s_add_u32 m0, s100, 22016
	ds_read_b128 v[198:201], v209 offset:58368
	global_load_lds_dwordx4 v[110:111], off offset:512
	s_waitcnt lgkmcnt(1)
	v_mfma_f32_32x32x16_f16 v[48:63], v[178:181], v[194:197], v[48:63]
	v_mfma_f32_32x32x16_f16 v[32:47], v[186:189], v[194:197], v[32:47]
	ds_read_b128 v[178:181], v206 offset:46080
	ds_read_b128 v[186:189], v206 offset:41984
	ds_read_b128 v[194:197], v210 offset:58368
	s_waitcnt lgkmcnt(3)
	v_mfma_f32_32x32x16_f16 v[48:63], v[182:185], v[198:201], v[48:63]
	v_mfma_f32_32x32x16_f16 v[32:47], v[190:193], v[198:201], v[32:47]
	ds_read_b128 v[182:185], v207 offset:46080
	ds_read_b128 v[190:193], v207 offset:41984
	ds_read_b128 v[198:201], v211 offset:58368
	s_waitcnt lgkmcnt(3)
	v_mfma_f32_32x32x16_f16 v[48:63], v[186:189], v[194:197], v[48:63]
	v_mfma_f32_32x32x16_f16 v[32:47], v[178:181], v[194:197], v[32:47]
	s_waitcnt lgkmcnt(0)
	v_mfma_f32_32x32x16_f16 v[48:63], v[190:193], v[198:201], v[48:63]
	v_mfma_f32_32x32x16_f16 v[32:47], v[182:185], v[198:201], v[32:47]
	s_waitcnt vmcnt(0)
	s_barrier
	s_add_u32 m0, s100, 41344
	ds_read_b128 v[178:181], v204 offset:2048
	global_load_lds_dwordx4 v[100:101], off offset:640
	s_add_u32 m0, s100, 45440
	ds_read_b128 v[182:185], v205 offset:2048
	global_load_lds_dwordx4 v[102:103], off offset:640
	s_add_u32 m0, s100, 49536
	ds_read_b128 v[186:189], v204 offset:6144
	global_load_lds_dwordx4 v[104:105], off offset:640
	s_add_u32 m0, s100, 53632
	ds_read_b128 v[190:193], v205 offset:6144
	global_load_lds_dwordx4 v[106:107], off offset:640
	s_add_u32 m0, s100, 57728
	ds_read_b128 v[194:197], v208 offset:18432
	global_load_lds_dwordx4 v[108:109], off offset:640
	s_add_u32 m0, s100, 61824
	ds_read_b128 v[198:201], v209 offset:18432
	global_load_lds_dwordx4 v[110:111], off offset:640
	s_waitcnt lgkmcnt(1)
	v_mfma_f32_32x32x16_f16 v[48:63], v[178:181], v[194:197], v[48:63]
	v_mfma_f32_32x32x16_f16 v[32:47], v[186:189], v[194:197], v[32:47]
	ds_read_b128 v[178:181], v206 offset:6144
	ds_read_b128 v[186:189], v206 offset:2048
	ds_read_b128 v[194:197], v210 offset:18432
	s_waitcnt lgkmcnt(3)
	v_mfma_f32_32x32x16_f16 v[48:63], v[182:185], v[198:201], v[48:63]
	v_mfma_f32_32x32x16_f16 v[32:47], v[190:193], v[198:201], v[32:47]
	ds_read_b128 v[182:185], v207 offset:6144
	ds_read_b128 v[190:193], v207 offset:2048
	ds_read_b128 v[198:201], v211 offset:18432
	s_waitcnt lgkmcnt(3)
	v_mfma_f32_32x32x16_f16 v[48:63], v[186:189], v[194:197], v[48:63]
	v_mfma_f32_32x32x16_f16 v[32:47], v[178:181], v[194:197], v[32:47]
	s_waitcnt lgkmcnt(0)
	v_mfma_f32_32x32x16_f16 v[48:63], v[190:193], v[198:201], v[48:63]
	v_mfma_f32_32x32x16_f16 v[32:47], v[182:185], v[198:201], v[32:47]
	s_waitcnt vmcnt(0)
	s_barrier
	s_add_u32 m0, s100, 1280
	s_nop 0
	global_load_lds_dwordx4 v[100:101], off offset:768
	s_add_u32 m0, s100, 5376
	s_nop 0
	global_load_lds_dwordx4 v[102:103], off offset:768
	s_add_u32 m0, s100, 9472
	s_nop 0
	global_load_lds_dwordx4 v[104:105], off offset:768
	s_add_u32 m0, s100, 13568
	s_nop 0
	global_load_lds_dwordx4 v[106:107], off offset:768
	s_add_u32 m0, s100, 17664
	s_nop 0
	global_load_lds_dwordx4 v[108:109], off offset:768
	s_add_u32 m0, s100, 21760
	ds_read_b128 v[124:127], v204 offset:41984
	global_load_lds_dwordx4 v[110:111], off offset:768
	ds_read_b128 v[128:131], v205 offset:41984
	ds_read_b128 v[134:137], v204 offset:46080
	ds_read_b128 v[178:181], v205 offset:46080
	ds_read_b128 v[182:185], v208 offset:58368
	ds_read_b128 v[186:189], v209 offset:58368
	s_waitcnt lgkmcnt(1)
	v_mfma_f32_32x32x16_f16 v[48:63], v[124:127], v[182:185], v[48:63]
	v_mfma_f32_32x32x16_f16 v[32:47], v[134:137], v[182:185], v[32:47]
	ds_read_b128 v[124:127], v206 offset:46080
	ds_read_b128 v[134:137], v206 offset:41984
	ds_read_b128 v[182:185], v210 offset:58368
	s_waitcnt lgkmcnt(3)
	v_mfma_f32_32x32x16_f16 v[48:63], v[128:131], v[186:189], v[48:63]
	v_mfma_f32_32x32x16_f16 v[32:47], v[178:181], v[186:189], v[32:47]
	ds_read_b128 v[128:131], v207 offset:46080
	ds_read_b128 v[178:181], v207 offset:41984
	ds_read_b128 v[186:189], v211 offset:58368
	s_waitcnt lgkmcnt(3)
	v_mfma_f32_32x32x16_f16 v[48:63], v[134:137], v[182:185], v[48:63]
	v_mfma_f32_32x32x16_f16 v[32:47], v[124:127], v[182:185], v[32:47]
	s_waitcnt lgkmcnt(0)
	v_mfma_f32_32x32x16_f16 v[48:63], v[178:181], v[186:189], v[48:63]
	v_mfma_f32_32x32x16_f16 v[32:47], v[128:131], v[186:189], v[32:47]
	s_waitcnt vmcnt(0)
	s_barrier
; DI float sigmoidf_(float x) { return __builtin_amdgcn_rcpf(1.f + __expf(-x)); }
; #define G_LOAD(RA, RB, k_) do { \
;     _Pragma("unroll") for (int i = 0; i < 4; ++i) RA[i] = *(const u32x4*)&Ap[i * sa + (k_)]; \
;     _Pragma("unroll") for (int i = 0; i < 2 * NJ; ++i) RB[i] = *(const u32x4*)&Bp[i * sbb + (k_)]; } while (0)
; template <int NJ>
; DI void gemm_core(const h16* __restrict__ A, int lda, const h16* __restrict__ Bt, int ldb, int K,
;                   floatx16 (&acc)[2][NJ], h16* As, h16* Bs) {
;     ...
;   G_LOAD(ra0, rb0, 0);
;   if (64 < K) G_LOAD(ra1, rb1, 64);
;   for (int k0 = 0; k0 < K; k0 += 128) {
;     G_STEP(ra0, rb0, k0 + 128);
;     if (k0 + 64 < K) G_STEP(ra1, rb1, k0 + 192);
; __global__ void __launch_bounds__(256, 2) mega(Params p) {
;     ...
; #pragma unroll
;         for (int i = 0; i < 2; ++i)
; #pragma unroll
;           for (int r = 0; r < 16; ++r) mg[i][0][r] += sigmoidf_(ag[i][0][r]) * ap[i][0][r];
	s_add_u32 m0, s100, 41088
	ds_read_b128 v[124:127], v204 offset:2048
	global_load_lds_dwordx4 v[100:101], off offset:896
	s_add_u32 m0, s100, 45184
	ds_read_b128 v[128:131], v205 offset:2048
	global_load_lds_dwordx4 v[102:103], off offset:896
	s_add_u32 m0, s100, 49280
	ds_read_b128 v[134:137], v204 offset:6144
	global_load_lds_dwordx4 v[104:105], off offset:896
	s_add_u32 m0, s100, 53376
	ds_read_b128 v[138:141], v205 offset:6144
	global_load_lds_dwordx4 v[106:107], off offset:896
	s_add_u32 m0, s100, 57472
	ds_read_b128 v[142:145], v208 offset:18432
	global_load_lds_dwordx4 v[108:109], off offset:896
	s_add_u32 m0, s100, 61568
	ds_read_b128 v[146:149], v209 offset:18432
	global_load_lds_dwordx4 v[110:111], off offset:896
	s_waitcnt lgkmcnt(1)
	v_mfma_f32_32x32x16_f16 v[48:63], v[124:127], v[142:145], v[48:63]
	v_mfma_f32_32x32x16_f16 v[32:47], v[134:137], v[142:145], v[32:47]
	ds_read_b128 v[124:127], v206 offset:6144
	ds_read_b128 v[134:137], v206 offset:2048
	ds_read_b128 v[142:145], v210 offset:18432
	s_waitcnt lgkmcnt(3)
	v_mfma_f32_32x32x16_f16 v[48:63], v[128:131], v[146:149], v[48:63]
	v_mfma_f32_32x32x16_f16 v[32:47], v[138:141], v[146:149], v[32:47]
	ds_read_b128 v[128:131], v207 offset:6144
	ds_read_b128 v[138:141], v207 offset:2048
	ds_read_b128 v[146:149], v211 offset:18432
	s_waitcnt lgkmcnt(3)
	v_mfma_f32_32x32x16_f16 v[48:63], v[134:137], v[142:145], v[48:63]
	v_mfma_f32_32x32x16_f16 v[32:47], v[124:127], v[142:145], v[32:47]
	s_waitcnt lgkmcnt(0)
	v_mfma_f32_32x32x16_f16 v[48:63], v[138:141], v[146:149], v[48:63]
	v_mfma_f32_32x32x16_f16 v[32:47], v[128:131], v[146:149], v[32:47]
	s_waitcnt vmcnt(0)
	s_barrier
	ds_read_b128 v[100:103], v204 offset:41984
	ds_read_b128 v[104:107], v205 offset:41984
	ds_read_b128 v[108:111], v204 offset:46080
	ds_read_b128 v[112:115], v205 offset:46080
	ds_read_b128 v[116:119], v208 offset:58368
	ds_read_b128 v[120:123], v209 offset:58368
	s_waitcnt lgkmcnt(1)
	v_mfma_f32_32x32x16_f16 v[48:63], v[100:103], v[116:119], v[48:63]
	v_mfma_f32_32x32x16_f16 v[32:47], v[108:111], v[116:119], v[32:47]
	ds_read_b128 v[100:103], v206 offset:46080
	ds_read_b128 v[108:111], v206 offset:41984
	ds_read_b128 v[116:119], v210 offset:58368
	s_waitcnt lgkmcnt(3)
	v_mfma_f32_32x32x16_f16 v[48:63], v[104:107], v[120:123], v[48:63]
	v_mfma_f32_32x32x16_f16 v[32:47], v[112:115], v[120:123], v[32:47]
	ds_read_b128 v[104:107], v207 offset:46080
	ds_read_b128 v[96:99], v207 offset:41984
	ds_read_b128 v[112:115], v211 offset:58368
	s_waitcnt lgkmcnt(3)
	v_mfma_f32_32x32x16_f16 v[48:63], v[108:111], v[116:119], v[48:63]
	v_mfma_f32_32x32x16_f16 v[32:47], v[100:103], v[116:119], v[32:47]
	s_waitcnt lgkmcnt(0)
	v_mfma_f32_32x32x16_f16 v[48:63], v[96:99], v[112:115], v[48:63]
	v_mfma_f32_32x32x16_f16 v[32:47], v[104:107], v[112:115], v[32:47]
	v_mul_f32_e32 v16, 0xbfb8aa3b, v16
	v_mul_f32_e32 v17, 0xbfb8aa3b, v17
	v_mul_f32_e32 v0, 0xbfb8aa3b, v0
	v_mul_f32_e32 v1, 0xbfb8aa3b, v1
	v_exp_f32_e32 v16, v16
	v_exp_f32_e32 v17, v17
	v_exp_f32_e32 v0, v0
	v_exp_f32_e32 v1, v1
	v_add_f32_e32 v16, 1.0, v16
	v_add_f32_e32 v17, 1.0, v17
	v_mul_f32_e32 v18, 0xbfb8aa3b, v18
	v_mul_f32_e32 v19, 0xbfb8aa3b, v19
	v_add_f32_e32 v0, 1.0, v0
	v_add_f32_e32 v1, 1.0, v1
	v_mul_f32_e32 v2, 0xbfb8aa3b, v2
	v_mul_f32_e32 v3, 0xbfb8aa3b, v3
	v_rcp_f32_e32 v16, v16
	v_rcp_f32_e32 v17, v17
	v_exp_f32_e32 v18, v18
	v_exp_f32_e32 v19, v19
	v_rcp_f32_e32 v0, v0
	v_rcp_f32_e32 v1, v1
	v_exp_f32_e32 v2, v2
	v_exp_f32_e32 v3, v3
	v_pk_fma_f32 v[94:95], v[16:17], v[48:49], v[94:95]
	v_add_f32_e32 v16, 1.0, v18
	v_add_f32_e32 v17, 1.0, v19
	v_mul_f32_e32 v18, 0xbfb8aa3b, v20
	v_mul_f32_e32 v19, 0xbfb8aa3b, v21
	v_pk_fma_f32 v[78:79], v[0:1], v[32:33], v[78:79]
	v_add_f32_e32 v0, 1.0, v2
	v_add_f32_e32 v1, 1.0, v3
	v_mul_f32_e32 v2, 0xbfb8aa3b, v4
	v_mul_f32_e32 v3, 0xbfb8aa3b, v5
	v_rcp_f32_e32 v16, v16
	v_rcp_f32_e32 v17, v17
	v_exp_f32_e32 v18, v18
	v_exp_f32_e32 v19, v19
	v_rcp_f32_e32 v0, v0
	v_rcp_f32_e32 v1, v1
	v_exp_f32_e32 v2, v2
	v_exp_f32_e32 v3, v3
	v_pk_fma_f32 v[92:93], v[16:17], v[50:51], v[92:93]
	v_add_f32_e32 v16, 1.0, v18
	v_add_f32_e32 v17, 1.0, v19
	v_mul_f32_e32 v18, 0xbfb8aa3b, v22
	v_mul_f32_e32 v19, 0xbfb8aa3b, v23
	v_pk_fma_f32 v[76:77], v[0:1], v[34:35], v[76:77]
	v_add_f32_e32 v0, 1.0, v2
	v_add_f32_e32 v1, 1.0, v3
	v_mul_f32_e32 v2, 0xbfb8aa3b, v6
	v_mul_f32_e32 v3, 0xbfb8aa3b, v7
	v_rcp_f32_e32 v16, v16
	v_rcp_f32_e32 v17, v17
	v_exp_f32_e32 v18, v18
	v_exp_f32_e32 v19, v19
	v_rcp_f32_e32 v0, v0
	v_rcp_f32_e32 v1, v1
	v_exp_f32_e32 v2, v2
	v_exp_f32_e32 v3, v3
	v_pk_fma_f32 v[90:91], v[16:17], v[52:53], v[90:91]
	v_add_f32_e32 v16, 1.0, v18
	v_add_f32_e32 v17, 1.0, v19
	v_mul_f32_e32 v18, 0xbfb8aa3b, v24
	v_mul_f32_e32 v19, 0xbfb8aa3b, v25
	v_pk_fma_f32 v[74:75], v[0:1], v[36:37], v[74:75]
	v_add_f32_e32 v0, 1.0, v2
	v_add_f32_e32 v1, 1.0, v3
	v_mul_f32_e32 v2, 0xbfb8aa3b, v8
	v_mul_f32_e32 v3, 0xbfb8aa3b, v9
	v_rcp_f32_e32 v16, v16
	v_rcp_f32_e32 v17, v17
	v_exp_f32_e32 v18, v18
	v_exp_f32_e32 v19, v19
	v_rcp_f32_e32 v0, v0
	v_rcp_f32_e32 v1, v1
	v_exp_f32_e32 v2, v2
	v_exp_f32_e32 v3, v3
	v_pk_fma_f32 v[88:89], v[16:17], v[54:55], v[88:89]
	v_add_f32_e32 v16, 1.0, v18
	v_add_f32_e32 v17, 1.0, v19
	v_mul_f32_e32 v18, 0xbfb8aa3b, v26
	v_mul_f32_e32 v19, 0xbfb8aa3b, v27
	v_pk_fma_f32 v[72:73], v[0:1], v[38:39], v[72:73]
	v_add_f32_e32 v0, 1.0, v2
	v_add_f32_e32 v1, 1.0, v3
	v_mul_f32_e32 v2, 0xbfb8aa3b, v10
	v_mul_f32_e32 v3, 0xbfb8aa3b, v11
	v_rcp_f32_e32 v16, v16
	v_rcp_f32_e32 v17, v17
	v_exp_f32_e32 v18, v18
	v_exp_f32_e32 v19, v19
	v_rcp_f32_e32 v0, v0
	v_rcp_f32_e32 v1, v1
	v_exp_f32_e32 v2, v2
	v_exp_f32_e32 v3, v3
; DI int otid() { int t = threadIdx.x; asm volatile("" : "+v"(t)); return t; }
; DI float sigmoidf_(float x) { return __builtin_amdgcn_rcpf(1.f + __expf(-x)); }
; template <int NJ, class F>
; DI void epi_apply(const floatx16 (&acc)[2][NJ], F f) {
;   const int t = otid(), l = t & 63, w = t >> 6, wm = w >> 1, wn = w & 1, h = l >> 5, lr = l & 31;
; #pragma unroll
;   for (int i = 0; i < 2; ++i)
; #pragma unroll
;     for (int j = 0; j < NJ; ++j)
; #pragma unroll
;       for (int r = 0; r < 16; ++r) {
;         f(wm * 64 + i * 32 + (r & 3) + 8 * (r >> 2) + 4 * h, wn * 32 * NJ + j * 32 + lr, acc[i][j][r]);
;         if ((r & 3) == 3) __builtin_amdgcn_sched_barrier(0);
;       }
; __global__ void __launch_bounds__(256, 2) mega(Params p) {
;     ...
;         for (int i = 0; i < 2; ++i)
; #pragma unroll
;           for (int r = 0; r < 16; ++r) mg[i][0][r] += sigmoidf_(ag[i][0][r]) * ap[i][0][r];
;       }
;       epi_apply<1>(mg, [&](int r, int c, float v) { merged[(size_t)(m0 + r) * 1024 + n0 + c] = (h16)v; });
	v_pk_fma_f32 v[86:87], v[16:17], v[56:57], v[86:87]
	v_add_f32_e32 v16, 1.0, v18
	v_add_f32_e32 v17, 1.0, v19
	v_mul_f32_e32 v18, 0xbfb8aa3b, v28
	v_mul_f32_e32 v19, 0xbfb8aa3b, v29
	v_pk_fma_f32 v[70:71], v[0:1], v[40:41], v[70:71]
	v_add_f32_e32 v0, 1.0, v2
	v_add_f32_e32 v1, 1.0, v3
	v_mul_f32_e32 v2, 0xbfb8aa3b, v12
	v_mul_f32_e32 v3, 0xbfb8aa3b, v13
	v_rcp_f32_e32 v16, v16
	v_rcp_f32_e32 v17, v17
	v_exp_f32_e32 v18, v18
	v_exp_f32_e32 v19, v19
	v_rcp_f32_e32 v0, v0
	v_rcp_f32_e32 v1, v1
	v_exp_f32_e32 v2, v2
	v_exp_f32_e32 v3, v3
	v_pk_fma_f32 v[84:85], v[16:17], v[58:59], v[84:85]
	v_add_f32_e32 v16, 1.0, v18
	v_add_f32_e32 v17, 1.0, v19
	v_mul_f32_e32 v18, 0xbfb8aa3b, v30
	v_mul_f32_e32 v19, 0xbfb8aa3b, v31
	v_pk_fma_f32 v[68:69], v[0:1], v[42:43], v[68:69]
	v_add_f32_e32 v0, 1.0, v2
	v_add_f32_e32 v1, 1.0, v3
	v_mul_f32_e32 v2, 0xbfb8aa3b, v14
	v_mul_f32_e32 v3, 0xbfb8aa3b, v15
	v_rcp_f32_e32 v16, v16
	v_rcp_f32_e32 v17, v17
	v_exp_f32_e32 v18, v18
	v_exp_f32_e32 v19, v19
	v_rcp_f32_e32 v0, v0
	v_rcp_f32_e32 v1, v1
	v_exp_f32_e32 v2, v2
	v_exp_f32_e32 v3, v3
	v_pk_fma_f32 v[82:83], v[16:17], v[60:61], v[82:83]
	v_add_f32_e32 v16, 1.0, v18
	v_add_f32_e32 v17, 1.0, v19
	v_pk_fma_f32 v[66:67], v[0:1], v[44:45], v[66:67]
	v_add_f32_e32 v0, 1.0, v2
	v_add_f32_e32 v1, 1.0, v3
	s_add_i32 s64, s64, 1
	v_rcp_f32_e32 v16, v16
	v_rcp_f32_e32 v17, v17
	v_rcp_f32_e32 v0, v0
	v_rcp_f32_e32 v1, v1
	s_add_u32 s44, s44, 0x100000
	s_addc_u32 s45, s45, 0
	s_add_u32 s47, s47, 0x200000
	s_addc_u32 s53, s53, 0
	v_pk_fma_f32 v[80:81], v[16:17], v[62:63], v[80:81]
	s_cmp_eq_u32 s64, 3
	v_pk_fma_f32 v[64:65], v[0:1], v[46:47], v[64:65]
	s_cbranch_scc0 .LBB0_984
	v_mov_b32_e32 v0, v152
	s_and_b32 s42, s60, 8
	v_ashrrev_i32_e32 v2, 1, v0
	v_and_b32_e32 v1, 31, v0
	v_and_b32_e32 v2, 0xffffffc0, v2
	v_lshrrev_b32_e32 v3, 3, v0
	v_lshrrev_b32_e32 v0, 1, v0
	v_and_or_b32 v4, v0, 32, v1
	v_and_or_b32 v0, v3, 4, v2
	v_add_u32_e32 v0, s46, v0
	s_and_b32 s43, s41, 7
	v_ashrrev_i32_e32 v1, 31, v0
	s_or_b32 s42, s42, s43
	v_cvt_f16_f32_e32 v5, v94
	v_lshlrev_b64 v[2:3], 11, v[0:1]
	v_lshl_add_u64 v[2:3], s[36:37], 0, v[2:3]
	s_lshl_b32 s76, s42, 7
	v_lshl_add_u64 v[2:3], v[2:3], 0, s[76:77]
	v_lshlrev_b32_e32 v132, 1, v4
	v_lshl_add_u64 v[2:3], v[2:3], 0, v[132:133]
	global_store_short v[2:3], v5, off
	v_add_u32_e32 v2, 1, v0
	v_ashrrev_i32_e32 v3, 31, v2
	v_cvt_f16_f32_e32 v1, v95
	v_lshlrev_b64 v[2:3], 11, v[2:3]
	v_lshl_add_u64 v[2:3], s[36:37], 0, v[2:3]
	v_lshl_add_u64 v[2:3], v[2:3], 0, s[76:77]
	v_lshl_add_u64 v[2:3], v[2:3], 0, v[132:133]
	global_store_short v[2:3], v1, off
	v_add_u32_e32 v2, 2, v0
	v_ashrrev_i32_e32 v3, 31, v2
	v_cvt_f16_f32_e32 v1, v92
	v_lshlrev_b64 v[2:3], 11, v[2:3]
	v_lshl_add_u64 v[2:3], s[36:37], 0, v[2:3]
	v_lshl_add_u64 v[2:3], v[2:3], 0, s[76:77]
	v_lshl_add_u64 v[2:3], v[2:3], 0, v[132:133]
	global_store_short v[2:3], v1, off
	v_add_u32_e32 v2, 3, v0
	v_ashrrev_i32_e32 v3, 31, v2
	v_cvt_f16_f32_e32 v1, v93
	v_lshlrev_b64 v[2:3], 11, v[2:3]
	v_lshl_add_u64 v[2:3], s[36:37], 0, v[2:3]
	v_lshl_add_u64 v[2:3], v[2:3], 0, s[76:77]
	s_mov_b32 s35, 0xfffffc0
	s_mov_b32 s33, 0x30000
	s_mov_b32 s59, 0x20000
	v_lshl_add_u64 v[2:3], v[2:3], 0, v[132:133]
	global_store_short v[2:3], v1, off
	v_add_u32_e32 v2, 8, v0
	v_ashrrev_i32_e32 v3, 31, v2
	v_cvt_f16_f32_e32 v1, v90
	v_lshlrev_b64 v[2:3], 11, v[2:3]
	v_lshl_add_u64 v[2:3], s[36:37], 0, v[2:3]
	v_lshl_add_u64 v[2:3], v[2:3], 0, s[76:77]
	v_lshl_add_u64 v[2:3], v[2:3], 0, v[132:133]
	global_store_short v[2:3], v1, off
	v_add_u32_e32 v2, 9, v0
	v_ashrrev_i32_e32 v3, 31, v2
	v_cvt_f16_f32_e32 v1, v91
	v_lshlrev_b64 v[2:3], 11, v[2:3]
	v_lshl_add_u64 v[2:3], s[36:37], 0, v[2:3]
	v_lshl_add_u64 v[2:3], v[2:3], 0, s[76:77]
	v_lshl_add_u64 v[2:3], v[2:3], 0, v[132:133]
	global_store_short v[2:3], v1, off
	v_add_u32_e32 v2, 10, v0
	v_ashrrev_i32_e32 v3, 31, v2
	v_cvt_f16_f32_e32 v1, v88
	v_lshlrev_b64 v[2:3], 11, v[2:3]
	v_lshl_add_u64 v[2:3], s[36:37], 0, v[2:3]
	v_lshl_add_u64 v[2:3], v[2:3], 0, s[76:77]
	v_lshl_add_u64 v[2:3], v[2:3], 0, v[132:133]
	global_store_short v[2:3], v1, off
	v_add_u32_e32 v2, 11, v0
	v_ashrrev_i32_e32 v3, 31, v2
	v_cvt_f16_f32_e32 v1, v89
	v_lshlrev_b64 v[2:3], 11, v[2:3]
	v_lshl_add_u64 v[2:3], s[36:37], 0, v[2:3]
	v_lshl_add_u64 v[2:3], v[2:3], 0, s[76:77]
	v_lshl_add_u64 v[2:3], v[2:3], 0, v[132:133]
	global_store_short v[2:3], v1, off
	v_add_u32_e32 v2, 16, v0
	v_ashrrev_i32_e32 v3, 31, v2
	v_cvt_f16_f32_e32 v1, v86
	v_lshlrev_b64 v[2:3], 11, v[2:3]
	v_lshl_add_u64 v[2:3], s[36:37], 0, v[2:3]
	v_lshl_add_u64 v[2:3], v[2:3], 0, s[76:77]
	v_lshl_add_u64 v[2:3], v[2:3], 0, v[132:133]
	global_store_short v[2:3], v1, off
	v_add_u32_e32 v2, 17, v0
	v_ashrrev_i32_e32 v3, 31, v2
	v_cvt_f16_f32_e32 v1, v87
	v_lshlrev_b64 v[2:3], 11, v[2:3]
	v_lshl_add_u64 v[2:3], s[36:37], 0, v[2:3]
	v_lshl_add_u64 v[2:3], v[2:3], 0, s[76:77]
	v_lshl_add_u64 v[2:3], v[2:3], 0, v[132:133]
	global_store_short v[2:3], v1, off
	v_add_u32_e32 v2, 18, v0
	v_ashrrev_i32_e32 v3, 31, v2
	v_cvt_f16_f32_e32 v1, v84
	v_lshlrev_b64 v[2:3], 11, v[2:3]
	v_lshl_add_u64 v[2:3], s[36:37], 0, v[2:3]
	v_lshl_add_u64 v[2:3], v[2:3], 0, s[76:77]
	v_lshl_add_u64 v[2:3], v[2:3], 0, v[132:133]
	global_store_short v[2:3], v1, off
	v_add_u32_e32 v2, 19, v0
	v_ashrrev_i32_e32 v3, 31, v2
	v_cvt_f16_f32_e32 v1, v85
	v_lshlrev_b64 v[2:3], 11, v[2:3]
	v_lshl_add_u64 v[2:3], s[36:37], 0, v[2:3]
	v_lshl_add_u64 v[2:3], v[2:3], 0, s[76:77]
	v_lshl_add_u64 v[2:3], v[2:3], 0, v[132:133]
	global_store_short v[2:3], v1, off
	v_add_u32_e32 v2, 24, v0
	v_ashrrev_i32_e32 v3, 31, v2
	v_cvt_f16_f32_e32 v1, v82
; DI int otid() { int t = threadIdx.x; asm volatile("" : "+v"(t)); return t; }
; template <int NJ, class F>
; DI void epi_apply(const floatx16 (&acc)[2][NJ], F f) {
;   const int t = otid(), l = t & 63, w = t >> 6, wm = w >> 1, wn = w & 1, h = l >> 5, lr = l & 31;
; #pragma unroll
;   for (int i = 0; i < 2; ++i)
; #pragma unroll
;     for (int j = 0; j < NJ; ++j)
; #pragma unroll
;       for (int r = 0; r < 16; ++r) {
;         f(wm * 64 + i * 32 + (r & 3) + 8 * (r >> 2) + 4 * h, wn * 32 * NJ + j * 32 + lr, acc[i][j][r]);
;         if ((r & 3) == 3) __builtin_amdgcn_sched_barrier(0);
;       }
; __global__ void __launch_bounds__(256, 2) mega(Params p) {
;     ...
;     if (PH(13)) for (int lj = xj.r; lj < 64 * 16; lj += xj.nrank) {
;       int mt, nt; xjob_map(xj, lj, 512, 16, mt, nt); const int m0 = mt * 128, n0 = nt * 64;
	v_lshlrev_b64 v[2:3], 11, v[2:3]
	v_lshl_add_u64 v[2:3], s[36:37], 0, v[2:3]
	v_lshl_add_u64 v[2:3], v[2:3], 0, s[76:77]
	v_lshl_add_u64 v[2:3], v[2:3], 0, v[132:133]
	global_store_short v[2:3], v1, off
	v_add_u32_e32 v2, 25, v0
	v_ashrrev_i32_e32 v3, 31, v2
	v_cvt_f16_f32_e32 v1, v83
	v_lshlrev_b64 v[2:3], 11, v[2:3]
	v_lshl_add_u64 v[2:3], s[36:37], 0, v[2:3]
	v_lshl_add_u64 v[2:3], v[2:3], 0, s[76:77]
	v_lshl_add_u64 v[2:3], v[2:3], 0, v[132:133]
	global_store_short v[2:3], v1, off
	v_add_u32_e32 v2, 26, v0
	v_ashrrev_i32_e32 v3, 31, v2
	v_cvt_f16_f32_e32 v1, v80
	v_lshlrev_b64 v[2:3], 11, v[2:3]
	v_lshl_add_u64 v[2:3], s[36:37], 0, v[2:3]
	v_lshl_add_u64 v[2:3], v[2:3], 0, s[76:77]
	v_lshl_add_u64 v[2:3], v[2:3], 0, v[132:133]
	global_store_short v[2:3], v1, off
	v_add_u32_e32 v2, 27, v0
	v_ashrrev_i32_e32 v3, 31, v2
	v_cvt_f16_f32_e32 v1, v81
	v_lshlrev_b64 v[2:3], 11, v[2:3]
	v_lshl_add_u64 v[2:3], s[36:37], 0, v[2:3]
	v_lshl_add_u64 v[2:3], v[2:3], 0, s[76:77]
	v_lshl_add_u64 v[2:3], v[2:3], 0, v[132:133]
	global_store_short v[2:3], v1, off
	v_add_u32_e32 v2, 32, v0
	v_ashrrev_i32_e32 v3, 31, v2
	v_cvt_f16_f32_e32 v1, v78
	v_lshlrev_b64 v[2:3], 11, v[2:3]
	v_lshl_add_u64 v[2:3], s[36:37], 0, v[2:3]
	v_lshl_add_u64 v[2:3], v[2:3], 0, s[76:77]
	v_lshl_add_u64 v[2:3], v[2:3], 0, v[132:133]
	global_store_short v[2:3], v1, off
	v_add_u32_e32 v2, 33, v0
	v_ashrrev_i32_e32 v3, 31, v2
	v_cvt_f16_f32_e32 v1, v79
	v_lshlrev_b64 v[2:3], 11, v[2:3]
	v_lshl_add_u64 v[2:3], s[36:37], 0, v[2:3]
	v_lshl_add_u64 v[2:3], v[2:3], 0, s[76:77]
	v_lshl_add_u64 v[2:3], v[2:3], 0, v[132:133]
	global_store_short v[2:3], v1, off
	v_add_u32_e32 v2, 34, v0
	v_ashrrev_i32_e32 v3, 31, v2
	v_cvt_f16_f32_e32 v1, v76
	v_lshlrev_b64 v[2:3], 11, v[2:3]
	v_lshl_add_u64 v[2:3], s[36:37], 0, v[2:3]
	v_lshl_add_u64 v[2:3], v[2:3], 0, s[76:77]
	v_lshl_add_u64 v[2:3], v[2:3], 0, v[132:133]
	global_store_short v[2:3], v1, off
	v_add_u32_e32 v2, 35, v0
	v_ashrrev_i32_e32 v3, 31, v2
	v_cvt_f16_f32_e32 v1, v77
	v_lshlrev_b64 v[2:3], 11, v[2:3]
	v_lshl_add_u64 v[2:3], s[36:37], 0, v[2:3]
	v_lshl_add_u64 v[2:3], v[2:3], 0, s[76:77]
	v_lshl_add_u64 v[2:3], v[2:3], 0, v[132:133]
	global_store_short v[2:3], v1, off
	v_add_u32_e32 v2, 40, v0
	v_ashrrev_i32_e32 v3, 31, v2
	v_cvt_f16_f32_e32 v1, v74
	v_lshlrev_b64 v[2:3], 11, v[2:3]
	v_lshl_add_u64 v[2:3], s[36:37], 0, v[2:3]
	v_lshl_add_u64 v[2:3], v[2:3], 0, s[76:77]
	v_lshl_add_u64 v[2:3], v[2:3], 0, v[132:133]
	global_store_short v[2:3], v1, off
	v_add_u32_e32 v2, 41, v0
	v_ashrrev_i32_e32 v3, 31, v2
	v_cvt_f16_f32_e32 v1, v75
	v_lshlrev_b64 v[2:3], 11, v[2:3]
	v_lshl_add_u64 v[2:3], s[36:37], 0, v[2:3]
	v_lshl_add_u64 v[2:3], v[2:3], 0, s[76:77]
	v_lshl_add_u64 v[2:3], v[2:3], 0, v[132:133]
	global_store_short v[2:3], v1, off
	v_add_u32_e32 v2, 42, v0
	v_ashrrev_i32_e32 v3, 31, v2
	v_cvt_f16_f32_e32 v1, v72
	v_lshlrev_b64 v[2:3], 11, v[2:3]
	v_lshl_add_u64 v[2:3], s[36:37], 0, v[2:3]
	v_lshl_add_u64 v[2:3], v[2:3], 0, s[76:77]
	v_lshl_add_u64 v[2:3], v[2:3], 0, v[132:133]
	global_store_short v[2:3], v1, off
	v_add_u32_e32 v2, 43, v0
	v_ashrrev_i32_e32 v3, 31, v2
	v_cvt_f16_f32_e32 v1, v73
	v_lshlrev_b64 v[2:3], 11, v[2:3]
	v_lshl_add_u64 v[2:3], s[36:37], 0, v[2:3]
	v_lshl_add_u64 v[2:3], v[2:3], 0, s[76:77]
	v_lshl_add_u64 v[2:3], v[2:3], 0, v[132:133]
	global_store_short v[2:3], v1, off
	v_add_u32_e32 v2, 48, v0
	v_ashrrev_i32_e32 v3, 31, v2
	v_cvt_f16_f32_e32 v1, v70
	v_lshlrev_b64 v[2:3], 11, v[2:3]
	v_lshl_add_u64 v[2:3], s[36:37], 0, v[2:3]
	v_lshl_add_u64 v[2:3], v[2:3], 0, s[76:77]
	v_lshl_add_u64 v[2:3], v[2:3], 0, v[132:133]
	global_store_short v[2:3], v1, off
	v_add_u32_e32 v2, 49, v0
	v_ashrrev_i32_e32 v3, 31, v2
	v_cvt_f16_f32_e32 v1, v71
	v_lshlrev_b64 v[2:3], 11, v[2:3]
	v_lshl_add_u64 v[2:3], s[36:37], 0, v[2:3]
	v_lshl_add_u64 v[2:3], v[2:3], 0, s[76:77]
	v_lshl_add_u64 v[2:3], v[2:3], 0, v[132:133]
	global_store_short v[2:3], v1, off
	v_add_u32_e32 v2, 50, v0
	v_ashrrev_i32_e32 v3, 31, v2
	v_cvt_f16_f32_e32 v1, v68
	v_lshlrev_b64 v[2:3], 11, v[2:3]
	v_lshl_add_u64 v[2:3], s[36:37], 0, v[2:3]
	v_lshl_add_u64 v[2:3], v[2:3], 0, s[76:77]
	v_lshl_add_u64 v[2:3], v[2:3], 0, v[132:133]
	global_store_short v[2:3], v1, off
	v_add_u32_e32 v2, 51, v0
	v_ashrrev_i32_e32 v3, 31, v2
	v_cvt_f16_f32_e32 v1, v69
	v_lshlrev_b64 v[2:3], 11, v[2:3]
	v_lshl_add_u64 v[2:3], s[36:37], 0, v[2:3]
	v_lshl_add_u64 v[2:3], v[2:3], 0, s[76:77]
	v_lshl_add_u64 v[2:3], v[2:3], 0, v[132:133]
	global_store_short v[2:3], v1, off
	v_add_u32_e32 v2, 56, v0
	v_ashrrev_i32_e32 v3, 31, v2
	v_cvt_f16_f32_e32 v1, v66
	v_lshlrev_b64 v[2:3], 11, v[2:3]
	v_lshl_add_u64 v[2:3], s[36:37], 0, v[2:3]
	v_lshl_add_u64 v[2:3], v[2:3], 0, s[76:77]
	v_lshl_add_u64 v[2:3], v[2:3], 0, v[132:133]
	global_store_short v[2:3], v1, off
	v_add_u32_e32 v2, 57, v0
	v_ashrrev_i32_e32 v3, 31, v2
	v_cvt_f16_f32_e32 v1, v67
	v_lshlrev_b64 v[2:3], 11, v[2:3]
	v_lshl_add_u64 v[2:3], s[36:37], 0, v[2:3]
	v_lshl_add_u64 v[2:3], v[2:3], 0, s[76:77]
	v_lshl_add_u64 v[2:3], v[2:3], 0, v[132:133]
	global_store_short v[2:3], v1, off
	v_add_u32_e32 v2, 58, v0
	v_ashrrev_i32_e32 v3, 31, v2
	v_cvt_f16_f32_e32 v1, v64
	v_lshlrev_b64 v[2:3], 11, v[2:3]
	v_lshl_add_u64 v[2:3], s[36:37], 0, v[2:3]
	v_lshl_add_u64 v[2:3], v[2:3], 0, s[76:77]
	v_lshl_add_u64 v[2:3], v[2:3], 0, v[132:133]
	v_add_u32_e32 v0, 59, v0
	global_store_short v[2:3], v1, off
	v_ashrrev_i32_e32 v1, 31, v0
	v_cvt_f16_f32_e32 v2, v65
	v_lshlrev_b64 v[0:1], 11, v[0:1]
	v_lshl_add_u64 v[0:1], s[36:37], 0, v[0:1]
	v_lshl_add_u64 v[0:1], v[0:1], 0, s[76:77]
	v_lshl_add_u64 v[0:1], v[0:1], 0, v[132:133]
	global_store_short v[0:1], v2, off
	s_add_i32 s41, s41, s34
	s_add_i32 s40, s40, s34
	s_cmpk_gt_u32 s41, 0x3ff
	s_cbranch_scc0 .LBB0_983
